# P0: non-temporal (nt) loads for the read-once f32 inputs (x, mem, weights)
# speedup vs baseline: 1.0159x; 1.0159x over previous
.LBB0_21:
	s_cmpk_gt_i32 s38, 0x1ff
	s_mov_b64 s[4:5], -1
	s_cbranch_scc0 .LBB0_123
	s_cmpk_gt_u32 s38, 0x57f
	s_cbranch_scc0 .LBB0_96
	s_cmpk_gt_u32 s38, 0x5df
	s_cbranch_scc0 .LBB0_89
	s_cmpk_gt_u32 s38, 0x6df
	s_cbranch_scc0 .LBB0_62
	s_cmpk_gt_u32 s38, 0x8df
	s_cbranch_scc0 .LBB0_59
	s_cmpk_gt_u32 s38, 0xcdf
	s_cbranch_scc0 .LBB0_56
	s_cmpk_gt_u32 s38, 0x22df
	s_cbranch_scc0 .LBB0_29
	s_add_i32 s4, s38, 0xffffdd20
	s_add_i32 s5, s38, 0xffffd7a0
	s_cmpk_lt_u32 s4, 0x580
	v_mov_b32_e32 v7, s0
	v_mov_b32_e32 v8, s1
	s_cselect_b32 s20, s4, s5
	s_cmpk_gt_u32 s4, 0x57f
	v_mov_b32_e32 v4, s0
	v_readfirstlane_b32 s4, v7
	v_readfirstlane_b32 s5, v8
	s_load_dwordx2 s[4:5], s[4:5], 0xb0
	v_mov_b32_e32 v6, s1
	s_cselect_b32 s8, 0xb00000, 0
	v_readfirstlane_b32 s18, v4
	v_readfirstlane_b32 s19, v6
	s_load_dwordx2 s[18:19], s[18:19], 0xc0
	s_cselect_b32 s21, 0x580000, 0
	s_waitcnt lgkmcnt(0)
	s_add_u32 s22, s4, s8
	s_addc_u32 s23, s5, 0
	s_lshl_b32 s4, s20, 1
	s_and_b32 s8, s4, 0xfc0
	s_lshl_b32 s4, s20, 5
	s_and_b32 s4, s4, 0x3e0
	s_add_u32 s18, s18, s21
	s_addc_u32 s5, s19, 0
	s_lshl_b32 s19, s4, 2
	s_add_u32 s20, s22, s19
	v_or_b32_e32 v8, s8, v3
	s_addc_u32 s21, s23, 0
	v_lshlrev_b32_e32 v4, 2, v0
	v_lshl_add_u64 v[6:7], s[20:21], 0, v[4:5]
	v_lshlrev_b32_e32 v4, 12, v8
	v_lshl_add_u64 v[6:7], v[6:7], 0, v[4:5]
	v_add_co_u32_e32 v8, vcc, s35, v6
	s_lshl_b32 s8, s8, 1
	s_nop 0
	v_addc_co_u32_e32 v9, vcc, 0, v7, vcc
	v_add_co_u32_e32 v10, vcc, s36, v6
	s_add_u32 s18, s18, s8
	s_nop 0
	v_addc_co_u32_e32 v11, vcc, 0, v7, vcc
	v_add_co_u32_e32 v12, vcc, s37, v6
	s_addc_u32 s19, s5, 0
	s_nop 0
	v_addc_co_u32_e32 v13, vcc, 0, v7, vcc
	v_add_co_u32_e32 v14, vcc, s74, v6
	s_nop 1
	v_addc_co_u32_e32 v15, vcc, 0, v7, vcc
	v_add_co_u32_e32 v16, vcc, s39, v6
	s_nop 1
	v_addc_co_u32_e32 v17, vcc, 0, v7, vcc
	v_add_co_u32_e32 v18, vcc, s40, v6
	s_nop 1
	v_addc_co_u32_e32 v19, vcc, 0, v7, vcc
	v_add_co_u32_e32 v20, vcc, s41, v6
	s_nop 1
	v_addc_co_u32_e32 v21, vcc, 0, v7, vcc
	global_load_dword v4, v[6:7], off nt
	global_load_dword v24, v[8:9], off nt
	global_load_dword v25, v[10:11], off nt
	global_load_dword v81, v[12:13], off nt
	global_load_dword v82, v[14:15], off nt
	global_load_dword v83, v[16:17], off nt
	global_load_dword v84, v[18:19], off nt
	global_load_dword v85, v[20:21], off nt
	v_add_co_u32_e32 v8, vcc, s42, v6
	s_nop 1
	v_addc_co_u32_e32 v9, vcc, 0, v7, vcc
	v_add_co_u32_e32 v10, vcc, s43, v6
	s_nop 1
	v_addc_co_u32_e32 v11, vcc, 0, v7, vcc
	v_add_co_u32_e32 v12, vcc, s44, v6
	s_nop 1
	v_addc_co_u32_e32 v13, vcc, 0, v7, vcc
	v_add_co_u32_e32 v14, vcc, s45, v6
	s_nop 1
	v_addc_co_u32_e32 v15, vcc, 0, v7, vcc
	v_add_co_u32_e32 v16, vcc, s46, v6
	s_nop 1
	v_addc_co_u32_e32 v17, vcc, 0, v7, vcc
	v_add_co_u32_e32 v18, vcc, s47, v6
	s_nop 1
	v_addc_co_u32_e32 v19, vcc, 0, v7, vcc
	v_add_co_u32_e32 v20, vcc, s48, v6
	s_nop 1
	v_addc_co_u32_e32 v21, vcc, 0, v7, vcc
	v_add_co_u32_e32 v22, vcc, s49, v6
	s_nop 1
	v_addc_co_u32_e32 v23, vcc, 0, v7, vcc
	global_load_dword v87, v[8:9], off nt
	global_load_dword v88, v[10:11], off nt
	global_load_dword v89, v[12:13], off nt
	global_load_dword v90, v[14:15], off nt
	global_load_dword v91, v[16:17], off nt
	global_load_dword v92, v[18:19], off nt
	global_load_dword v93, v[20:21], off nt
	global_load_dword v94, v[22:23], off nt
	v_add_co_u32_e32 v8, vcc, s50, v6
	s_nop 1
	v_addc_co_u32_e32 v9, vcc, 0, v7, vcc
	v_add_co_u32_e32 v10, vcc, s51, v6
	s_nop 1
	v_addc_co_u32_e32 v11, vcc, 0, v7, vcc
	v_add_co_u32_e32 v12, vcc, s52, v6
	s_nop 1
	v_addc_co_u32_e32 v13, vcc, 0, v7, vcc
	v_add_co_u32_e32 v14, vcc, s53, v6
	s_nop 1
	v_addc_co_u32_e32 v15, vcc, 0, v7, vcc
	v_add_co_u32_e32 v16, vcc, s54, v6
	s_nop 1
	v_addc_co_u32_e32 v17, vcc, 0, v7, vcc
	v_add_co_u32_e32 v18, vcc, s55, v6
	s_nop 1
	v_addc_co_u32_e32 v19, vcc, 0, v7, vcc
	v_add_co_u32_e32 v20, vcc, s56, v6
	s_nop 1
	v_addc_co_u32_e32 v21, vcc, 0, v7, vcc
	v_add_co_u32_e32 v22, vcc, s57, v6
	s_nop 1
	v_addc_co_u32_e32 v23, vcc, 0, v7, vcc
	global_load_dword v95, v[8:9], off nt
	global_load_dword v96, v[10:11], off nt
	global_load_dword v97, v[12:13], off nt
	global_load_dword v98, v[14:15], off nt
	global_load_dword v99, v[16:17], off nt
	global_load_dword v100, v[18:19], off nt
	global_load_dword v101, v[20:21], off nt
	s_nop 0
	global_load_dword v22, v[22:23], off nt
	v_add_co_u32_e32 v8, vcc, s58, v6
	s_nop 1
	v_addc_co_u32_e32 v9, vcc, 0, v7, vcc
	v_add_co_u32_e32 v10, vcc, s59, v6
	s_nop 1
	v_addc_co_u32_e32 v11, vcc, 0, v7, vcc
	v_add_co_u32_e32 v12, vcc, s60, v6
	s_nop 1
	v_addc_co_u32_e32 v13, vcc, 0, v7, vcc
	v_add_co_u32_e32 v14, vcc, s61, v6
	s_nop 1
	v_addc_co_u32_e32 v15, vcc, 0, v7, vcc
	v_add_co_u32_e32 v16, vcc, s62, v6
	s_nop 1
	v_addc_co_u32_e32 v17, vcc, 0, v7, vcc
	v_add_co_u32_e32 v18, vcc, s63, v6
	s_nop 1
	v_addc_co_u32_e32 v19, vcc, 0, v7, vcc
	v_add_co_u32_e32 v20, vcc, s64, v6
	s_nop 1
	v_addc_co_u32_e32 v21, vcc, 0, v7, vcc
	v_add_co_u32_e32 v6, vcc, s65, v6
	s_nop 1
	v_addc_co_u32_e32 v7, vcc, 0, v7, vcc
	global_load_dword v8, v[8:9], off nt
	s_nop 0
	global_load_dword v9, v[10:11], off nt
	s_nop 0
	global_load_dword v10, v[12:13], off nt
	global_load_dword v11, v[14:15], off nt
	s_nop 0
	global_load_dword v12, v[16:17], off nt
	global_load_dword v13, v[18:19], off nt
	global_load_dword v14, v[20:21], off nt
	s_nop 0
	global_load_dword v6, v[6:7], off nt
	s_waitcnt vmcnt(30)
	ds_write2_b32 v27, v4, v24 offset1:66
	s_waitcnt vmcnt(28)
	ds_write2_b32 v27, v25, v81 offset0:132 offset1:198
	v_add_u32_e32 v4, 0x400, v27
	s_waitcnt vmcnt(26)
	ds_write2_b32 v4, v82, v83 offset0:8 offset1:74
	s_waitcnt vmcnt(24)
	ds_write2_b32 v4, v84, v85 offset0:140 offset1:206
	v_add_u32_e32 v4, 0x800, v27
	s_waitcnt vmcnt(22)
	ds_write2_b32 v4, v87, v88 offset0:16 offset1:82
	s_waitcnt vmcnt(20)
	ds_write2_b32 v4, v89, v90 offset0:148 offset1:214
	v_add_u32_e32 v4, 0xc00, v27
	s_waitcnt vmcnt(18)
	ds_write2_b32 v4, v91, v92 offset0:24 offset1:90
	s_waitcnt vmcnt(16)
	ds_write2_b32 v4, v93, v94 offset0:156 offset1:222
	v_add_u32_e32 v4, 0x1000, v27
	s_waitcnt vmcnt(14)
	ds_write2_b32 v4, v95, v96 offset0:32 offset1:98
	s_waitcnt vmcnt(12)
	ds_write2_b32 v4, v97, v98 offset0:164 offset1:230
	v_add_u32_e32 v4, 0x1400, v27
	s_waitcnt vmcnt(10)
	ds_write2_b32 v4, v99, v100 offset0:40 offset1:106
	s_waitcnt vmcnt(8)
	ds_write2_b32 v4, v101, v22 offset0:172 offset1:238
	v_add_u32_e32 v4, 0x1800, v27
	s_waitcnt vmcnt(6)
	ds_write2_b32 v4, v8, v9 offset0:48 offset1:114
	s_waitcnt vmcnt(4)
	ds_write2_b32 v4, v10, v11 offset0:180 offset1:246
	v_add_u32_e32 v4, 0x1c00, v27
	s_waitcnt vmcnt(2)
	ds_write2_b32 v4, v12, v13 offset0:56 offset1:122
	s_waitcnt vmcnt(0)
	ds_write2_b32 v4, v14, v6 offset0:188 offset1:254
	s_waitcnt lgkmcnt(0)
	v_lshlrev_b32_e32 v4, 1, v2
	ds_read2_b32 v[6:7], v29 offset1:33
	v_lshl_add_u64 v[12:13], s[18:19], 0, v[4:5]
	v_or_b32_e32 v4, s4, v28
	s_waitcnt lgkmcnt(0)
	v_cvt_pk_bf16_f32 v6, v6, v7
	ds_read2_b32 v[8:9], v29 offset0:66 offset1:99
	s_mov_b64 s[18:19], 0x23e0000
	v_mul_u32_u24_e32 v4, 0xb00, v4
	s_waitcnt lgkmcnt(0)
	v_cvt_pk_bf16_f32 v7, v8, v9
	ds_read2_b32 v[8:9], v29 offset0:132 offset1:165
	v_lshl_add_u64 v[12:13], v[12:13], 0, s[18:19]
	v_lshlrev_b32_e32 v4, 1, v4
	s_waitcnt lgkmcnt(0)
	v_cvt_pk_bf16_f32 v8, v8, v9
	ds_read2_b32 v[10:11], v29 offset0:198 offset1:231
	s_waitcnt lgkmcnt(0)
	v_cvt_pk_bf16_f32 v9, v10, v11
	v_lshl_add_u64 v[14:15], v[12:13], 0, v[4:5]
	v_or_b32_e32 v4, s4, v30
	ds_read2_b32 v[10:11], v29 offset0:8 offset1:41
	global_store_dwordx4 v[14:15], v[6:9], off
	v_mul_u32_u24_e32 v4, 0xb00, v4
	v_lshlrev_b32_e32 v4, 1, v4
	s_waitcnt lgkmcnt(0)
	v_cvt_pk_bf16_f32 v6, v10, v11
	ds_read2_b32 v[8:9], v29 offset0:74 offset1:107
	s_waitcnt lgkmcnt(0)
	v_cvt_pk_bf16_f32 v7, v8, v9
	ds_read2_b32 v[8:9], v29 offset0:140 offset1:173
	s_waitcnt lgkmcnt(0)
	v_cvt_pk_bf16_f32 v8, v8, v9
	ds_read2_b32 v[10:11], v29 offset0:206 offset1:239
	s_waitcnt lgkmcnt(0)
	v_cvt_pk_bf16_f32 v9, v10, v11
	v_lshl_add_u64 v[14:15], v[12:13], 0, v[4:5]
	v_or_b32_e32 v4, s4, v31
	ds_read2_b32 v[10:11], v29 offset0:16 offset1:49
	global_store_dwordx4 v[14:15], v[6:9], off
	v_mul_u32_u24_e32 v4, 0xb00, v4
	v_lshlrev_b32_e32 v4, 1, v4
	s_waitcnt lgkmcnt(0)
	v_cvt_pk_bf16_f32 v6, v10, v11
	ds_read2_b32 v[8:9], v29 offset0:82 offset1:115
	s_waitcnt lgkmcnt(0)
	v_cvt_pk_bf16_f32 v7, v8, v9
	ds_read2_b32 v[8:9], v29 offset0:148 offset1:181
	s_waitcnt lgkmcnt(0)
	v_cvt_pk_bf16_f32 v8, v8, v9
	ds_read2_b32 v[10:11], v29 offset0:214 offset1:247
	s_waitcnt lgkmcnt(0)
	v_cvt_pk_bf16_f32 v9, v10, v11
	v_lshl_add_u64 v[14:15], v[12:13], 0, v[4:5]
	ds_read2_b32 v[10:11], v29 offset0:24 offset1:57
	global_store_dwordx4 v[14:15], v[6:9], off
	v_or_b32_e32 v4, s4, v32
	v_mul_u32_u24_e32 v4, 0xb00, v4
	s_waitcnt lgkmcnt(0)
	v_cvt_pk_bf16_f32 v6, v10, v11
	ds_read2_b32 v[8:9], v29 offset0:90 offset1:123
	s_waitcnt lgkmcnt(0)
	v_cvt_pk_bf16_f32 v7, v8, v9
	ds_read2_b32 v[8:9], v29 offset0:156 offset1:189
	s_waitcnt lgkmcnt(0)
	v_cvt_pk_bf16_f32 v8, v8, v9
	ds_read2_b32 v[10:11], v29 offset0:222 offset1:255
	v_lshlrev_b32_e32 v4, 1, v4
	s_waitcnt lgkmcnt(0)
	v_cvt_pk_bf16_f32 v9, v10, v11
	v_lshl_add_u64 v[10:11], v[12:13], 0, v[4:5]
	global_store_dwordx4 v[10:11], v[6:9], off
	s_waitcnt lgkmcnt(0)
	s_mov_b64 s[4:5], 0
.LBB0_29:
	s_andn2_b64 vcc, exec, s[4:5]
	s_cbranch_vccnz .LBB0_55
	s_add_i32 s4, s38, 0xfffff320
	s_cmpk_gt_u32 s4, 0xaff
	s_cselect_b64 s[18:19], -1, 0
	s_add_i32 s5, s38, 0xffffe820
	s_cmpk_lt_u32 s4, 0xb00
	s_cselect_b32 s8, s4, s5
	s_mul_hi_u32 s4, s8, 0xba2e8ba3
	v_mov_b32_e32 v7, s0
	v_mov_b32_e32 v8, s1
	s_lshr_b32 s22, s4, 7
	s_mul_i32 s23, s22, 0xb0
	v_readfirstlane_b32 s4, v7
	v_readfirstlane_b32 s5, v8
	s_load_dwordx2 s[20:21], s[4:5], 0xa8
	s_sub_i32 s73, s8, s23
	s_lshl_b32 s8, s73, 5
	s_and_b64 s[4:5], s[18:19], exec
	v_mov_b32_e32 v4, s0
	v_mov_b32_e32 v6, s1
	s_cselect_b32 s4, 0x1600000, 0
	v_mov_b32_e32 v23, s0
	v_mov_b32_e32 v108, s1
	s_waitcnt lgkmcnt(0)
	s_add_u32 s24, s20, s4
	s_addc_u32 s25, s21, 0
	v_readfirstlane_b32 s4, v4
	v_readfirstlane_b32 s5, v6
	s_load_dwordx2 s[4:5], s[4:5], 0x20
	s_lshl_b32 s72, s22, 6
	s_and_b64 s[20:21], s[18:19], exec
	s_cselect_b32 s20, 0x1000, 0
	v_or_b32_e32 v22, s72, v3
	s_waitcnt lgkmcnt(0)
	s_add_u32 s20, s4, s20
	s_addc_u32 s21, s5, 0
	s_lshl_b64 s[22:23], s[8:9], 2
	s_add_u32 s22, s24, s22
	s_addc_u32 s23, s25, s23
	v_lshlrev_b32_e32 v4, 2, v0
	v_lshl_add_u64 v[6:7], s[22:23], 0, v[4:5]
	v_or_b32_e32 v4, 2, v22
	v_mad_u64_u32 v[10:11], s[22:23], v4, s66, v[6:7]
	v_or_b32_e32 v4, 4, v22
	v_mad_u64_u32 v[12:13], s[22:23], v4, s66, v[6:7]
	v_or_b32_e32 v4, 6, v22
	v_mad_u64_u32 v[14:15], s[22:23], v4, s66, v[6:7]
	v_or_b32_e32 v4, 8, v22
	v_mad_u64_u32 v[16:17], s[22:23], v4, s66, v[6:7]
	v_or_b32_e32 v4, 10, v22
	v_mad_u64_u32 v[18:19], s[22:23], v4, s66, v[6:7]
	v_or_b32_e32 v4, 12, v22
	v_mad_u64_u32 v[24:25], s[22:23], v4, s66, v[6:7]
	v_or_b32_e32 v4, 14, v22
	v_mad_u64_u32 v[8:9], s[22:23], v22, s66, v[6:7]
	v_mad_u64_u32 v[82:83], s[22:23], v4, s66, v[6:7]
	v_or_b32_e32 v4, 16, v22
	global_load_dword v95, v[8:9], off nt
	global_load_dword v94, v[10:11], off nt
	global_load_dword v20, v[12:13], off nt
	global_load_dword v21, v[14:15], off nt
	global_load_dword v92, v[16:17], off nt
	global_load_dword v93, v[18:19], off nt
	s_nop 0
	global_load_dword v18, v[24:25], off nt
	global_load_dword v19, v[82:83], off nt
	v_mad_u64_u32 v[8:9], s[22:23], v4, s66, v[6:7]
	v_or_b32_e32 v4, 18, v22
	v_mad_u64_u32 v[10:11], s[22:23], v4, s66, v[6:7]
	v_or_b32_e32 v4, 20, v22
	v_mad_u64_u32 v[12:13], s[22:23], v4, s66, v[6:7]
	v_or_b32_e32 v4, 22, v22
	v_mad_u64_u32 v[14:15], s[22:23], v4, s66, v[6:7]
	v_or_b32_e32 v4, 24, v22
	v_mad_u64_u32 v[24:25], s[22:23], v4, s66, v[6:7]
	v_or_b32_e32 v4, 26, v22
	v_mad_u64_u32 v[82:83], s[22:23], v4, s66, v[6:7]
	v_or_b32_e32 v4, 28, v22
	v_mad_u64_u32 v[84:85], s[22:23], v4, s66, v[6:7]
	v_or_b32_e32 v4, 30, v22
	v_mad_u64_u32 v[96:97], s[22:23], v4, s66, v[6:7]
	v_or_b32_e32 v4, 32, v22
	global_load_dword v90, v[8:9], off nt
	global_load_dword v91, v[10:11], off nt
	global_load_dword v16, v[12:13], off nt
	global_load_dword v17, v[14:15], off nt
	global_load_dword v88, v[24:25], off nt
	global_load_dword v89, v[82:83], off nt
	s_nop 0
	global_load_dword v14, v[84:85], off nt
	global_load_dword v15, v[96:97], off nt
	v_mad_u64_u32 v[8:9], s[22:23], v4, s66, v[6:7]
	v_or_b32_e32 v4, 34, v22
	v_mad_u64_u32 v[10:11], s[22:23], v4, s66, v[6:7]
	v_or_b32_e32 v4, 36, v22
	v_mad_u64_u32 v[12:13], s[22:23], v4, s66, v[6:7]
	v_or_b32_e32 v4, 38, v22
	v_mad_u64_u32 v[24:25], s[22:23], v4, s66, v[6:7]
	v_or_b32_e32 v4, 40, v22
	v_mad_u64_u32 v[82:83], s[22:23], v4, s66, v[6:7]
	v_or_b32_e32 v4, 42, v22
	v_mad_u64_u32 v[96:97], s[22:23], v4, s66, v[6:7]
	v_or_b32_e32 v4, 44, v22
	v_mad_u64_u32 v[98:99], s[22:23], v4, s66, v[6:7]
	v_or_b32_e32 v4, 46, v22
	v_mad_u64_u32 v[100:101], s[22:23], v4, s66, v[6:7]
	v_or_b32_e32 v4, 48, v22
	global_load_dword v85, v[8:9], off nt
	global_load_dword v87, v[10:11], off nt
	s_nop 0
	global_load_dword v12, v[12:13], off nt
	s_nop 0
	global_load_dword v13, v[24:25], off nt
	s_nop 0
	global_load_dword v83, v[82:83], off nt
	s_nop 0
	global_load_dword v84, v[96:97], off nt
	global_load_dword v10, v[98:99], off nt
	global_load_dword v11, v[100:101], off nt
	v_mad_u64_u32 v[8:9], s[22:23], v4, s66, v[6:7]
	v_or_b32_e32 v4, 50, v22
	v_mad_u64_u32 v[24:25], s[22:23], v4, s66, v[6:7]
	v_or_b32_e32 v4, 52, v22
	v_mad_u64_u32 v[96:97], s[22:23], v4, s66, v[6:7]
	v_or_b32_e32 v4, 54, v22
	v_mad_u64_u32 v[98:99], s[22:23], v4, s66, v[6:7]
	v_or_b32_e32 v4, 56, v22
	v_mad_u64_u32 v[100:101], s[22:23], v4, s66, v[6:7]
	v_or_b32_e32 v4, 58, v22
	v_mad_u64_u32 v[102:103], s[22:23], v4, s66, v[6:7]
	v_or_b32_e32 v4, 60, v22
	v_mad_u64_u32 v[104:105], s[22:23], v4, s66, v[6:7]
	v_or_b32_e32 v4, 62, v22
	v_mad_u64_u32 v[106:107], s[22:23], v4, s66, v[6:7]
	global_load_dword v81, v[8:9], off nt
	global_load_dword v82, v[24:25], off nt
	s_nop 0
	global_load_dword v8, v[96:97], off nt
	global_load_dword v9, v[98:99], off nt
	global_load_dword v24, v[100:101], off nt
	global_load_dword v25, v[102:103], off nt
	global_load_dword v6, v[104:105], off nt
	global_load_dword v7, v[106:107], off nt
	s_cmp_lg_u64 s[4:5], 0
	v_readfirstlane_b32 s22, v23
	v_readfirstlane_b32 s23, v108
	s_cselect_b64 s[24:25], -1, 0
	s_cmp_eq_u64 s[4:5], 0
	v_add_u32_e32 v4, s72, v3
	s_cbranch_scc1 .LBB0_141
	v_mov_b32_e32 v23, v5
	v_lshl_add_u64 v[96:97], v[4:5], 2, s[20:21]
	v_lshl_add_u64 v[22:23], v[22:23], 2, s[20:21]
	global_load_dword v100, v[96:97], off offset:8 nt
	global_load_dword v98, v[96:97], off offset:16 nt
	global_load_dword v99, v[96:97], off offset:24 nt
	s_nop 0
	global_load_dword v96, v[22:23], off nt
	v_add_u32_e32 v97, v26, v34
	s_waitcnt vmcnt(3)
	v_mul_f32_e32 v100, v94, v100
	s_waitcnt vmcnt(1)
	v_pk_mul_f32 v[22:23], v[20:21], v[98:99]
	s_waitcnt vmcnt(0)
	v_mul_f32_e32 v96, v95, v96
	ds_write_b32 v27, v96
	ds_write_b32 v97, v100
	s_load_dwordx2 s[22:23], s[22:23], 0xc0
	s_cbranch_execnz .LBB0_33

.LBB0_33:
	s_waitcnt vmcnt(28)
	v_cndmask_b32_e64 v21, 0, 1, s[24:25]
	v_add_u32_e32 v20, v26, v36
	v_cmp_ne_u32_e64 s[4:5], 1, v21
	s_andn2_b64 vcc, exec, s[24:25]
	ds_write2_b32 v20, v22, v23 offset1:66
	s_cbranch_vccnz .LBB0_142
	v_lshl_add_u64 v[20:21], v[4:5], 2, s[20:21]
	global_load_dword v94, v[20:21], off offset:32 nt
	global_load_dword v95, v[20:21], off offset:40 nt
	global_load_dword v22, v[20:21], off offset:48 nt
	global_load_dword v23, v[20:21], off offset:56 nt
	v_add_u32_e32 v96, v26, v39
	s_waitcnt vmcnt(3)
	v_mul_f32_e32 v94, v92, v94
	s_waitcnt vmcnt(2)
	v_mul_f32_e32 v95, v93, v95
	ds_write2_b32 v96, v94, v95 offset1:66
	s_waitcnt vmcnt(0)
	v_pk_mul_f32 v[20:21], v[18:19], v[22:23]
	s_cbranch_execnz .LBB0_36

.LBB0_36:
	s_waitcnt vmcnt(25)
	v_add_u32_e32 v18, v26, v42
	s_and_b64 vcc, exec, s[4:5]
	ds_write2_b32 v18, v20, v21 offset1:66
	s_cbranch_vccnz .LBB0_143
	s_waitcnt vmcnt(24)
	v_lshl_add_u64 v[18:19], v[4:5], 2, s[20:21]
	global_load_dword v22, v[18:19], off offset:64 nt
	global_load_dword v23, v[18:19], off offset:72 nt
	global_load_dword v20, v[18:19], off offset:80 nt
	global_load_dword v21, v[18:19], off offset:88 nt
	v_add_u32_e32 v92, v26, v45
	s_waitcnt vmcnt(3)
	v_mul_f32_e32 v22, v90, v22
	s_waitcnt vmcnt(2)
	v_mul_f32_e32 v23, v91, v23
	ds_write2_b32 v92, v22, v23 offset1:66
	s_waitcnt vmcnt(0)
	v_pk_mul_f32 v[18:19], v[16:17], v[20:21]
	s_cbranch_execnz .LBB0_39

.LBB0_39:
	s_waitcnt vmcnt(21)
	v_add_u32_e32 v16, v26, v48
	s_and_b64 vcc, exec, s[4:5]
	ds_write2_b32 v16, v18, v19 offset1:66
	s_cbranch_vccnz .LBB0_144
	s_waitcnt vmcnt(20)
	v_lshl_add_u64 v[16:17], v[4:5], 2, s[20:21]
	global_load_dword v20, v[16:17], off offset:96 nt
	global_load_dword v21, v[16:17], off offset:104 nt
	global_load_dword v18, v[16:17], off offset:112 nt
	global_load_dword v19, v[16:17], off offset:120 nt
	v_add_u32_e32 v22, v26, v51
	s_waitcnt vmcnt(3)
	v_mul_f32_e32 v20, v88, v20
	s_waitcnt vmcnt(2)
	v_mul_f32_e32 v21, v89, v21
	ds_write2_b32 v22, v20, v21 offset1:66
	s_waitcnt vmcnt(0)
	v_pk_mul_f32 v[16:17], v[14:15], v[18:19]
	s_cbranch_execnz .LBB0_42

.LBB0_42:
	s_waitcnt vmcnt(17)
	v_add_u32_e32 v14, v26, v54
	s_and_b64 vcc, exec, s[4:5]
	ds_write2_b32 v14, v16, v17 offset1:66
	s_cbranch_vccnz .LBB0_145
	s_waitcnt vmcnt(16)
	v_lshl_add_u64 v[14:15], v[4:5], 2, s[20:21]
	global_load_dword v18, v[14:15], off offset:128 nt
	global_load_dword v19, v[14:15], off offset:136 nt
	global_load_dword v16, v[14:15], off offset:144 nt
	global_load_dword v17, v[14:15], off offset:152 nt
	v_add_u32_e32 v20, v26, v57
	s_waitcnt vmcnt(3)
	v_mul_f32_e32 v18, v85, v18
	s_waitcnt vmcnt(2)
	v_mul_f32_e32 v19, v87, v19
	ds_write2_b32 v20, v18, v19 offset1:66
	s_waitcnt vmcnt(0)
	v_pk_mul_f32 v[14:15], v[12:13], v[16:17]
	s_cbranch_execnz .LBB0_45

.LBB0_45:
	s_waitcnt vmcnt(13)
	v_add_u32_e32 v12, v26, v60
	s_and_b64 vcc, exec, s[4:5]
	ds_write2_b32 v12, v14, v15 offset1:66
	s_cbranch_vccnz .LBB0_146
	s_waitcnt vmcnt(12)
	v_lshl_add_u64 v[12:13], v[4:5], 2, s[20:21]
	global_load_dword v16, v[12:13], off offset:160 nt
	global_load_dword v17, v[12:13], off offset:168 nt
	global_load_dword v14, v[12:13], off offset:176 nt
	global_load_dword v15, v[12:13], off offset:184 nt
	v_add_u32_e32 v18, v26, v63
	s_waitcnt vmcnt(3)
	v_mul_f32_e32 v16, v83, v16
	s_waitcnt vmcnt(2)
	v_mul_f32_e32 v17, v84, v17
	ds_write2_b32 v18, v16, v17 offset1:66
	s_waitcnt vmcnt(0)
	v_pk_mul_f32 v[12:13], v[10:11], v[14:15]
	s_cbranch_execnz .LBB0_48

.LBB0_48:
	s_waitcnt vmcnt(9)
	v_add_u32_e32 v10, v26, v66
	s_and_b64 vcc, exec, s[4:5]
	ds_write2_b32 v10, v12, v13 offset1:66
	s_cbranch_vccnz .LBB0_147
	s_waitcnt vmcnt(8)
	v_lshl_add_u64 v[10:11], v[4:5], 2, s[20:21]
	global_load_dword v14, v[10:11], off offset:192 nt
	global_load_dword v15, v[10:11], off offset:200 nt
	global_load_dword v12, v[10:11], off offset:208 nt
	global_load_dword v13, v[10:11], off offset:216 nt
	v_add_u32_e32 v16, v26, v69
	s_waitcnt vmcnt(3)
	v_mul_f32_e32 v14, v81, v14
	s_waitcnt vmcnt(2)
	v_mul_f32_e32 v15, v82, v15
	ds_write2_b32 v16, v14, v15 offset1:66
	s_waitcnt vmcnt(0)
	v_pk_mul_f32 v[10:11], v[8:9], v[12:13]
	s_cbranch_execnz .LBB0_51

.LBB0_51:
	s_waitcnt vmcnt(5)
	v_add_u32_e32 v8, v26, v69
	ds_write2_b32 v8, v10, v11 offset0:132 offset1:198
	s_and_b64 vcc, exec, s[4:5]
	v_add_u32_e32 v10, 0x400, v8
	s_cbranch_vccnz .LBB0_148
	s_waitcnt vmcnt(4)
	v_lshl_add_u64 v[8:9], v[4:5], 2, s[20:21]
	global_load_dword v4, v[8:9], off offset:224 nt
	global_load_dword v11, v[8:9], off offset:232 nt
	global_load_dword v12, v[8:9], off offset:240 nt
	global_load_dword v13, v[8:9], off offset:248 nt
	s_waitcnt vmcnt(3)
	v_mul_f32_e32 v4, v24, v4
	s_waitcnt vmcnt(2)
	v_mul_f32_e32 v11, v25, v11
	ds_write2_b32 v10, v4, v11 offset0:8 offset1:74
	s_waitcnt vmcnt(0)
	v_pk_mul_f32 v[8:9], v[6:7], v[12:13]
	s_cbranch_execnz .LBB0_54

.LBB0_56:
	s_andn2_b64 vcc, exec, s[4:5]
	s_cbranch_vccnz .LBB0_58
	v_mov_b32_e32 v7, s1
	v_mov_b32_e32 v8, s0
	s_add_i32 s8, s38, 0xfffff720
	v_readfirstlane_b32 s4, v8
	v_readfirstlane_b32 s5, v7
	s_load_dwordx2 s[4:5], s[4:5], 0xa0
	s_lshr_b32 s8, s8, 9
	s_lshl_b64 s[18:19], s[8:9], 22
	v_mov_b32_e32 v4, s0
	v_mov_b32_e32 v6, s1
	s_waitcnt lgkmcnt(0)
	s_add_u32 s24, s4, s18
	s_addc_u32 s19, s5, s19
	s_lshl_b64 s[22:23], s[8:9], 21
	v_readfirstlane_b32 s4, v4
	v_readfirstlane_b32 s5, v6
	s_load_dwordx2 s[20:21], s[4:5], 0xc0
	s_add_i32 s4, s7, 0xffffee40
	s_and_b32 s18, s4, 0x3c0
	s_and_b32 s4, s27, 0x3e0
	v_or_b32_e32 v8, s18, v3
	s_waitcnt lgkmcnt(0)
	s_add_u32 s8, s20, s22
	s_addc_u32 s5, s21, s23
	s_lshl_b32 s20, s4, 2
	s_add_u32 s20, s24, s20
	s_addc_u32 s21, s19, 0
	v_lshlrev_b32_e32 v4, 2, v0
	v_lshl_add_u64 v[6:7], s[20:21], 0, v[4:5]
	v_lshlrev_b32_e32 v4, 12, v8
	v_lshl_add_u64 v[6:7], v[6:7], 0, v[4:5]
	v_add_co_u32_e32 v8, vcc, s35, v6
	s_lshl_b32 s18, s18, 1
	s_nop 0
	v_addc_co_u32_e32 v9, vcc, 0, v7, vcc
	v_add_co_u32_e32 v10, vcc, s36, v6
	s_add_u32 s18, s8, s18
	s_nop 0
	v_addc_co_u32_e32 v11, vcc, 0, v7, vcc
	v_add_co_u32_e32 v12, vcc, s37, v6
	s_addc_u32 s19, s5, 0
	s_nop 0
	v_addc_co_u32_e32 v13, vcc, 0, v7, vcc
	v_add_co_u32_e32 v14, vcc, s74, v6
	s_nop 1
	v_addc_co_u32_e32 v15, vcc, 0, v7, vcc
	v_add_co_u32_e32 v16, vcc, s39, v6
	s_nop 1
	v_addc_co_u32_e32 v17, vcc, 0, v7, vcc
	v_add_co_u32_e32 v18, vcc, s40, v6
	s_nop 1
	v_addc_co_u32_e32 v19, vcc, 0, v7, vcc
	v_add_co_u32_e32 v20, vcc, s41, v6
	s_nop 1
	v_addc_co_u32_e32 v21, vcc, 0, v7, vcc
	global_load_dword v4, v[6:7], off nt
	global_load_dword v24, v[8:9], off nt
	global_load_dword v25, v[10:11], off nt
	global_load_dword v81, v[12:13], off nt
	global_load_dword v82, v[14:15], off nt
	global_load_dword v83, v[16:17], off nt
	global_load_dword v84, v[18:19], off nt
	global_load_dword v85, v[20:21], off nt
	v_add_co_u32_e32 v8, vcc, s42, v6
	s_nop 1
	v_addc_co_u32_e32 v9, vcc, 0, v7, vcc
	v_add_co_u32_e32 v10, vcc, s43, v6
	s_nop 1
	v_addc_co_u32_e32 v11, vcc, 0, v7, vcc
	v_add_co_u32_e32 v12, vcc, s44, v6
	s_nop 1
	v_addc_co_u32_e32 v13, vcc, 0, v7, vcc
	v_add_co_u32_e32 v14, vcc, s45, v6
	s_nop 1
	v_addc_co_u32_e32 v15, vcc, 0, v7, vcc
	v_add_co_u32_e32 v16, vcc, s46, v6
	s_nop 1
	v_addc_co_u32_e32 v17, vcc, 0, v7, vcc
	v_add_co_u32_e32 v18, vcc, s47, v6
	s_nop 1
	v_addc_co_u32_e32 v19, vcc, 0, v7, vcc
	v_add_co_u32_e32 v20, vcc, s48, v6
	s_nop 1
	v_addc_co_u32_e32 v21, vcc, 0, v7, vcc
	v_add_co_u32_e32 v22, vcc, s49, v6
	s_nop 1
	v_addc_co_u32_e32 v23, vcc, 0, v7, vcc
	global_load_dword v87, v[8:9], off nt
	global_load_dword v88, v[10:11], off nt
	global_load_dword v89, v[12:13], off nt
	global_load_dword v90, v[14:15], off nt
	global_load_dword v91, v[16:17], off nt
	global_load_dword v92, v[18:19], off nt
	global_load_dword v93, v[20:21], off nt
	global_load_dword v94, v[22:23], off nt
	v_add_co_u32_e32 v8, vcc, s50, v6
	s_nop 1
	v_addc_co_u32_e32 v9, vcc, 0, v7, vcc
	v_add_co_u32_e32 v10, vcc, s51, v6
	s_nop 1
	v_addc_co_u32_e32 v11, vcc, 0, v7, vcc
	v_add_co_u32_e32 v12, vcc, s52, v6
	s_nop 1
	v_addc_co_u32_e32 v13, vcc, 0, v7, vcc
	v_add_co_u32_e32 v14, vcc, s53, v6
	s_nop 1
	v_addc_co_u32_e32 v15, vcc, 0, v7, vcc
	v_add_co_u32_e32 v16, vcc, s54, v6
	s_nop 1
	v_addc_co_u32_e32 v17, vcc, 0, v7, vcc
	v_add_co_u32_e32 v18, vcc, s55, v6
	s_nop 1
	v_addc_co_u32_e32 v19, vcc, 0, v7, vcc
	v_add_co_u32_e32 v20, vcc, s56, v6
	s_nop 1
	v_addc_co_u32_e32 v21, vcc, 0, v7, vcc
	v_add_co_u32_e32 v22, vcc, s57, v6
	s_nop 1
	v_addc_co_u32_e32 v23, vcc, 0, v7, vcc
	global_load_dword v95, v[8:9], off nt
	global_load_dword v96, v[10:11], off nt
	global_load_dword v97, v[12:13], off nt
	global_load_dword v98, v[14:15], off nt
	global_load_dword v99, v[16:17], off nt
	global_load_dword v100, v[18:19], off nt
	global_load_dword v101, v[20:21], off nt
	s_nop 0
	global_load_dword v22, v[22:23], off nt
	v_add_co_u32_e32 v8, vcc, s58, v6
	s_nop 1
	v_addc_co_u32_e32 v9, vcc, 0, v7, vcc
	v_add_co_u32_e32 v10, vcc, s59, v6
	s_nop 1
	v_addc_co_u32_e32 v11, vcc, 0, v7, vcc
	v_add_co_u32_e32 v12, vcc, s60, v6
	s_nop 1
	v_addc_co_u32_e32 v13, vcc, 0, v7, vcc
	v_add_co_u32_e32 v14, vcc, s61, v6
	s_nop 1
	v_addc_co_u32_e32 v15, vcc, 0, v7, vcc
	v_add_co_u32_e32 v16, vcc, s62, v6
	s_nop 1
	v_addc_co_u32_e32 v17, vcc, 0, v7, vcc
	v_add_co_u32_e32 v18, vcc, s63, v6
	s_nop 1
	v_addc_co_u32_e32 v19, vcc, 0, v7, vcc
	v_add_co_u32_e32 v20, vcc, s64, v6
	s_nop 1
	v_addc_co_u32_e32 v21, vcc, 0, v7, vcc
	v_add_co_u32_e32 v6, vcc, s65, v6
	s_nop 1
	v_addc_co_u32_e32 v7, vcc, 0, v7, vcc
	global_load_dword v8, v[8:9], off nt
	s_nop 0
	global_load_dword v9, v[10:11], off nt
	s_nop 0
	global_load_dword v10, v[12:13], off nt
	global_load_dword v11, v[14:15], off nt
	s_nop 0
	global_load_dword v12, v[16:17], off nt
	global_load_dword v13, v[18:19], off nt
	global_load_dword v14, v[20:21], off nt
	s_nop 0
	global_load_dword v6, v[6:7], off nt
	s_waitcnt vmcnt(30)
	ds_write2_b32 v27, v4, v24 offset1:66
	s_waitcnt vmcnt(28)
	ds_write2_b32 v27, v25, v81 offset0:132 offset1:198
	v_add_u32_e32 v4, 0x400, v27
	s_waitcnt vmcnt(26)
	ds_write2_b32 v4, v82, v83 offset0:8 offset1:74
	s_waitcnt vmcnt(24)
	ds_write2_b32 v4, v84, v85 offset0:140 offset1:206
	v_add_u32_e32 v4, 0x800, v27
	s_waitcnt vmcnt(22)
	ds_write2_b32 v4, v87, v88 offset0:16 offset1:82
	s_waitcnt vmcnt(20)
	ds_write2_b32 v4, v89, v90 offset0:148 offset1:214
	v_add_u32_e32 v4, 0xc00, v27
	s_waitcnt vmcnt(18)
	ds_write2_b32 v4, v91, v92 offset0:24 offset1:90
	s_waitcnt vmcnt(16)
	ds_write2_b32 v4, v93, v94 offset0:156 offset1:222
	v_add_u32_e32 v4, 0x1000, v27
	s_waitcnt vmcnt(14)
	ds_write2_b32 v4, v95, v96 offset0:32 offset1:98
	s_waitcnt vmcnt(12)
	ds_write2_b32 v4, v97, v98 offset0:164 offset1:230
	v_add_u32_e32 v4, 0x1400, v27
	s_waitcnt vmcnt(10)
	ds_write2_b32 v4, v99, v100 offset0:40 offset1:106
	s_waitcnt vmcnt(8)
	ds_write2_b32 v4, v101, v22 offset0:172 offset1:238
	v_add_u32_e32 v4, 0x1800, v27
	s_waitcnt vmcnt(6)
	ds_write2_b32 v4, v8, v9 offset0:48 offset1:114
	s_waitcnt vmcnt(4)
	ds_write2_b32 v4, v10, v11 offset0:180 offset1:246
	v_add_u32_e32 v4, 0x1c00, v27
	s_waitcnt vmcnt(2)
	ds_write2_b32 v4, v12, v13 offset0:56 offset1:122
	s_waitcnt vmcnt(0)
	ds_write2_b32 v4, v14, v6 offset0:188 offset1:254
	s_waitcnt lgkmcnt(0)
	ds_read2_b32 v[6:7], v29 offset1:33
	v_lshlrev_b32_e32 v4, 1, v2
	s_waitcnt lgkmcnt(0)
	v_cvt_pk_bf16_f32 v6, v6, v7
	ds_read2_b32 v[8:9], v29 offset0:66 offset1:99
	v_lshl_add_u64 v[12:13], s[18:19], 0, v[4:5]
	s_mov_b64 s[18:19], 0x9e0000
	v_or_b32_e32 v4, s4, v28
	s_waitcnt lgkmcnt(0)
	v_cvt_pk_bf16_f32 v7, v8, v9
	ds_read2_b32 v[8:9], v29 offset0:132 offset1:165
	v_lshl_add_u64 v[12:13], v[12:13], 0, s[18:19]
	v_lshlrev_b32_e32 v4, 11, v4
	s_waitcnt lgkmcnt(0)
	v_cvt_pk_bf16_f32 v8, v8, v9
	ds_read2_b32 v[10:11], v29 offset0:198 offset1:231
	s_waitcnt lgkmcnt(0)
	v_cvt_pk_bf16_f32 v9, v10, v11
	v_lshl_add_u64 v[14:15], v[12:13], 0, v[4:5]
	ds_read2_b32 v[10:11], v29 offset0:8 offset1:41
	global_store_dwordx4 v[14:15], v[6:9], off
	v_or_b32_e32 v4, s4, v30
	v_lshlrev_b32_e32 v4, 11, v4
	s_waitcnt lgkmcnt(0)
	v_cvt_pk_bf16_f32 v6, v10, v11
	ds_read2_b32 v[8:9], v29 offset0:74 offset1:107
	s_waitcnt lgkmcnt(0)
	v_cvt_pk_bf16_f32 v7, v8, v9
	ds_read2_b32 v[8:9], v29 offset0:140 offset1:173
	s_waitcnt lgkmcnt(0)
	v_cvt_pk_bf16_f32 v8, v8, v9
	ds_read2_b32 v[10:11], v29 offset0:206 offset1:239
	s_waitcnt lgkmcnt(0)
	v_cvt_pk_bf16_f32 v9, v10, v11
	v_lshl_add_u64 v[14:15], v[12:13], 0, v[4:5]
	ds_read2_b32 v[10:11], v29 offset0:16 offset1:49
	global_store_dwordx4 v[14:15], v[6:9], off
	v_or_b32_e32 v4, s4, v31
	v_lshlrev_b32_e32 v4, 11, v4
	s_waitcnt lgkmcnt(0)
	v_cvt_pk_bf16_f32 v6, v10, v11
	ds_read2_b32 v[8:9], v29 offset0:82 offset1:115
	s_waitcnt lgkmcnt(0)
	v_cvt_pk_bf16_f32 v7, v8, v9
	ds_read2_b32 v[8:9], v29 offset0:148 offset1:181
	s_waitcnt lgkmcnt(0)
	v_cvt_pk_bf16_f32 v8, v8, v9
	ds_read2_b32 v[10:11], v29 offset0:214 offset1:247
	s_waitcnt lgkmcnt(0)
	v_cvt_pk_bf16_f32 v9, v10, v11
	v_lshl_add_u64 v[14:15], v[12:13], 0, v[4:5]
	ds_read2_b32 v[10:11], v29 offset0:24 offset1:57
	global_store_dwordx4 v[14:15], v[6:9], off
	v_or_b32_e32 v4, s4, v32
	v_lshlrev_b32_e32 v4, 11, v4
	s_waitcnt lgkmcnt(0)
	v_cvt_pk_bf16_f32 v6, v10, v11
	ds_read2_b32 v[8:9], v29 offset0:90 offset1:123
	s_waitcnt lgkmcnt(0)
	v_cvt_pk_bf16_f32 v7, v8, v9
	ds_read2_b32 v[8:9], v29 offset0:156 offset1:189
	s_waitcnt lgkmcnt(0)
	v_cvt_pk_bf16_f32 v8, v8, v9
	ds_read2_b32 v[10:11], v29 offset0:222 offset1:255
	s_waitcnt lgkmcnt(0)
	v_cvt_pk_bf16_f32 v9, v10, v11
	v_lshl_add_u64 v[10:11], v[12:13], 0, v[4:5]
	global_store_dwordx4 v[10:11], v[6:9], off
	s_waitcnt lgkmcnt(0)

.LBB0_59:
	s_andn2_b64 vcc, exec, s[4:5]
	s_cbranch_vccnz .LBB0_61
	v_mov_b32_e32 v7, s0
	v_mov_b32_e32 v8, s1
	v_mov_b32_e32 v4, s0
	v_readfirstlane_b32 s4, v7
	v_readfirstlane_b32 s5, v8
	v_mov_b32_e32 v7, s0
	v_mov_b32_e32 v8, s1
	v_mov_b32_e32 v6, s1
	s_load_dwordx2 s[22:23], s[4:5], 0x90
	s_and_b32 s8, s7, 0x1fc0
	v_readfirstlane_b32 s4, v7
	v_readfirstlane_b32 s5, v8
	s_load_dwordx2 s[4:5], s[4:5], 0xc0
	s_and_b32 s21, s27, 0x3e0
	v_readfirstlane_b32 s18, v4
	v_readfirstlane_b32 s19, v6
	s_load_dwordx2 s[18:19], s[18:19], 0x10
	s_addk_i32 s8, 0xf240
	s_add_i32 s20, s21, 0x200
	v_or_b32_e32 v6, s8, v3
	v_lshlrev_b32_e32 v4, 2, v0
	s_waitcnt lgkmcnt(0)
	s_add_u32 s18, s18, 0x1000
	s_addc_u32 s19, s19, 0
	s_lshl_b32 s21, s21, 2
	s_add_u32 s22, s22, s21
	s_addc_u32 s23, s23, 0
	v_lshl_add_u64 v[8:9], s[22:23], 0, v[4:5]
	v_or_b32_e32 v4, 2, v6
	v_lshlrev_b64 v[12:13], 12, v[4:5]
	v_or_b32_e32 v4, 4, v6
	v_lshlrev_b64 v[14:15], 12, v[4:5]
	v_or_b32_e32 v4, 6, v6
	v_lshlrev_b64 v[16:17], 12, v[4:5]
	v_or_b32_e32 v4, 8, v6
	v_lshlrev_b64 v[18:19], 12, v[4:5]
	v_or_b32_e32 v4, 10, v6
	v_mov_b32_e32 v7, v5
	v_lshlrev_b64 v[20:21], 12, v[4:5]
	v_or_b32_e32 v4, 12, v6
	v_lshlrev_b64 v[10:11], 12, v[6:7]
	v_lshlrev_b64 v[22:23], 12, v[4:5]
	v_or_b32_e32 v4, 14, v6
	v_lshl_add_u64 v[10:11], v[8:9], 0, v[10:11]
	v_lshlrev_b64 v[24:25], 12, v[4:5]
	v_or_b32_e32 v4, 16, v6
	v_lshl_add_u64 v[12:13], v[8:9], 0, v[12:13]
	v_lshl_add_u64 v[14:15], v[8:9], 0, v[14:15]
	v_lshl_add_u64 v[16:17], v[8:9], 0, v[16:17]
	v_lshl_add_u64 v[18:19], v[8:9], 0, v[18:19]
	v_lshl_add_u64 v[20:21], v[8:9], 0, v[20:21]
	v_lshl_add_u64 v[22:23], v[8:9], 0, v[22:23]
	v_lshl_add_u64 v[24:25], v[8:9], 0, v[24:25]
	global_load_dword v81, v[10:11], off nt
	global_load_dword v82, v[12:13], off nt
	global_load_dword v83, v[14:15], off nt
	global_load_dword v84, v[16:17], off nt
	global_load_dword v85, v[18:19], off nt
	global_load_dword v87, v[20:21], off nt
	global_load_dword v88, v[22:23], off nt
	global_load_dword v89, v[24:25], off nt
	v_lshlrev_b64 v[10:11], 12, v[4:5]
	v_or_b32_e32 v4, 18, v6
	v_lshlrev_b64 v[12:13], 12, v[4:5]
	v_or_b32_e32 v4, 20, v6
	v_lshlrev_b64 v[14:15], 12, v[4:5]
	v_or_b32_e32 v4, 22, v6
	v_lshlrev_b64 v[16:17], 12, v[4:5]
	v_or_b32_e32 v4, 24, v6
	v_lshlrev_b64 v[18:19], 12, v[4:5]
	v_or_b32_e32 v4, 26, v6
	v_lshlrev_b64 v[20:21], 12, v[4:5]
	v_or_b32_e32 v4, 28, v6
	v_lshlrev_b64 v[22:23], 12, v[4:5]
	v_or_b32_e32 v4, 30, v6
	v_lshl_add_u64 v[10:11], v[8:9], 0, v[10:11]
	v_lshlrev_b64 v[24:25], 12, v[4:5]
	v_or_b32_e32 v4, 32, v6
	v_lshl_add_u64 v[12:13], v[8:9], 0, v[12:13]
	v_lshl_add_u64 v[14:15], v[8:9], 0, v[14:15]
	v_lshl_add_u64 v[16:17], v[8:9], 0, v[16:17]
	v_lshl_add_u64 v[18:19], v[8:9], 0, v[18:19]
	v_lshl_add_u64 v[20:21], v[8:9], 0, v[20:21]
	v_lshl_add_u64 v[22:23], v[8:9], 0, v[22:23]
	v_lshl_add_u64 v[24:25], v[8:9], 0, v[24:25]
	global_load_dword v90, v[10:11], off nt
	global_load_dword v91, v[12:13], off nt
	global_load_dword v92, v[14:15], off nt
	global_load_dword v93, v[16:17], off nt
	global_load_dword v94, v[18:19], off nt
	global_load_dword v95, v[20:21], off nt
	global_load_dword v96, v[22:23], off nt
	global_load_dword v97, v[24:25], off nt
	v_lshlrev_b64 v[10:11], 12, v[4:5]
	v_or_b32_e32 v4, 34, v6
	v_lshlrev_b64 v[12:13], 12, v[4:5]
	v_or_b32_e32 v4, 36, v6
	v_lshlrev_b64 v[14:15], 12, v[4:5]
	v_or_b32_e32 v4, 38, v6
	v_lshlrev_b64 v[16:17], 12, v[4:5]
	v_or_b32_e32 v4, 40, v6
	v_lshlrev_b64 v[18:19], 12, v[4:5]
	v_or_b32_e32 v4, 42, v6
	v_lshlrev_b64 v[20:21], 12, v[4:5]
	v_or_b32_e32 v4, 44, v6
	v_lshlrev_b64 v[22:23], 12, v[4:5]
	v_or_b32_e32 v4, 46, v6
	v_lshl_add_u64 v[10:11], v[8:9], 0, v[10:11]
	v_lshlrev_b64 v[24:25], 12, v[4:5]
	v_or_b32_e32 v4, 48, v6
	v_lshl_add_u64 v[12:13], v[8:9], 0, v[12:13]
	v_lshl_add_u64 v[14:15], v[8:9], 0, v[14:15]
	v_lshl_add_u64 v[16:17], v[8:9], 0, v[16:17]
	v_lshl_add_u64 v[18:19], v[8:9], 0, v[18:19]
	v_lshl_add_u64 v[20:21], v[8:9], 0, v[20:21]
	v_lshl_add_u64 v[22:23], v[8:9], 0, v[22:23]
	v_lshl_add_u64 v[24:25], v[8:9], 0, v[24:25]
	global_load_dword v98, v[10:11], off nt
	global_load_dword v99, v[12:13], off nt
	global_load_dword v100, v[14:15], off nt
	global_load_dword v101, v[16:17], off nt
	global_load_dword v102, v[18:19], off nt
	global_load_dword v103, v[20:21], off nt
	global_load_dword v104, v[22:23], off nt
	global_load_dword v105, v[24:25], off nt
	v_lshlrev_b64 v[10:11], 12, v[4:5]
	v_or_b32_e32 v4, 50, v6
	v_lshlrev_b64 v[12:13], 12, v[4:5]
	v_or_b32_e32 v4, 52, v6
	v_lshlrev_b64 v[14:15], 12, v[4:5]
	v_or_b32_e32 v4, 54, v6
	v_lshlrev_b64 v[16:17], 12, v[4:5]
	v_or_b32_e32 v4, 56, v6
	v_lshlrev_b64 v[18:19], 12, v[4:5]
	v_or_b32_e32 v4, 58, v6
	v_lshlrev_b64 v[20:21], 12, v[4:5]
	v_or_b32_e32 v4, 60, v6
	v_lshlrev_b64 v[22:23], 12, v[4:5]
	v_or_b32_e32 v4, 62, v6
	v_lshlrev_b64 v[24:25], 12, v[4:5]
	v_lshl_add_u64 v[10:11], v[8:9], 0, v[10:11]
	v_lshl_add_u64 v[12:13], v[8:9], 0, v[12:13]
	v_lshl_add_u64 v[14:15], v[8:9], 0, v[14:15]
	v_lshl_add_u64 v[16:17], v[8:9], 0, v[16:17]
	v_lshl_add_u64 v[18:19], v[8:9], 0, v[18:19]
	v_lshl_add_u64 v[20:21], v[8:9], 0, v[20:21]
	v_lshl_add_u64 v[22:23], v[8:9], 0, v[22:23]
	v_lshl_add_u64 v[8:9], v[8:9], 0, v[24:25]
	v_or_b32_e32 v4, s8, v33
	global_load_dword v24, v[10:11], off nt
	global_load_dword v25, v[12:13], off nt
	global_load_dword v106, v[14:15], off nt
	global_load_dword v107, v[16:17], off nt
	global_load_dword v108, v[18:19], off nt
	global_load_dword v109, v[20:21], off nt
	s_nop 0
	global_load_dword v22, v[22:23], off nt
	s_nop 0
	global_load_dword v23, v[8:9], off nt
	v_lshl_add_u64 v[8:9], v[4:5], 2, s[18:19]
	v_or_b32_e32 v4, s8, v35
	v_lshl_add_u64 v[10:11], v[4:5], 2, s[18:19]
	v_or_b32_e32 v4, s8, v37
	v_lshl_add_u64 v[12:13], v[4:5], 2, s[18:19]
	v_or_b32_e32 v4, s8, v38
	v_lshl_add_u64 v[14:15], v[4:5], 2, s[18:19]
	v_or_b32_e32 v4, s8, v40
	v_lshl_add_u64 v[16:17], v[4:5], 2, s[18:19]
	v_or_b32_e32 v4, s8, v41
	v_lshl_add_u64 v[18:19], v[4:5], 2, s[18:19]
	v_or_b32_e32 v4, s8, v43
	v_lshl_add_u64 v[6:7], v[6:7], 2, s[18:19]
	v_lshl_add_u64 v[20:21], v[4:5], 2, s[18:19]
	v_or_b32_e32 v4, s8, v44
	global_load_dword v110, v[6:7], off nt
	global_load_dword v111, v[8:9], off nt
	global_load_dword v112, v[10:11], off nt
	global_load_dword v113, v[12:13], off nt
	global_load_dword v114, v[14:15], off nt
	global_load_dword v115, v[16:17], off nt
	global_load_dword v116, v[18:19], off nt
	global_load_dword v117, v[20:21], off nt
	v_lshl_add_u64 v[6:7], v[4:5], 2, s[18:19]
	v_or_b32_e32 v4, s8, v46
	v_lshl_add_u64 v[8:9], v[4:5], 2, s[18:19]
	v_or_b32_e32 v4, s8, v47
	v_lshl_add_u64 v[10:11], v[4:5], 2, s[18:19]
	v_or_b32_e32 v4, s8, v49
	v_lshl_add_u64 v[12:13], v[4:5], 2, s[18:19]
	v_or_b32_e32 v4, s8, v50
	v_lshl_add_u64 v[14:15], v[4:5], 2, s[18:19]
	v_or_b32_e32 v4, s8, v52
	v_lshl_add_u64 v[16:17], v[4:5], 2, s[18:19]
	v_or_b32_e32 v4, s8, v53
	v_lshl_add_u64 v[18:19], v[4:5], 2, s[18:19]
	v_or_b32_e32 v4, s8, v55
	v_lshl_add_u64 v[20:21], v[4:5], 2, s[18:19]
	v_or_b32_e32 v4, s8, v56
	global_load_dword v118, v[6:7], off nt
	global_load_dword v119, v[8:9], off nt
	global_load_dword v120, v[10:11], off nt
	global_load_dword v121, v[12:13], off nt
	global_load_dword v122, v[14:15], off nt
	global_load_dword v123, v[16:17], off nt
	global_load_dword v124, v[18:19], off nt
	global_load_dword v125, v[20:21], off nt
	v_lshl_add_u64 v[6:7], v[4:5], 2, s[18:19]
	v_or_b32_e32 v4, s8, v58
	v_lshl_add_u64 v[8:9], v[4:5], 2, s[18:19]
	v_or_b32_e32 v4, s8, v59
	v_lshl_add_u64 v[10:11], v[4:5], 2, s[18:19]
	v_or_b32_e32 v4, s8, v61
	v_lshl_add_u64 v[12:13], v[4:5], 2, s[18:19]
	v_or_b32_e32 v4, s8, v62
	v_lshl_add_u64 v[14:15], v[4:5], 2, s[18:19]
	v_or_b32_e32 v4, s8, v64
	v_lshl_add_u64 v[16:17], v[4:5], 2, s[18:19]
	v_or_b32_e32 v4, s8, v65
	v_lshl_add_u64 v[18:19], v[4:5], 2, s[18:19]
	v_or_b32_e32 v4, s8, v67
	v_lshl_add_u64 v[20:21], v[4:5], 2, s[18:19]
	v_or_b32_e32 v4, s8, v68
	global_load_dword v126, v[6:7], off nt
	global_load_dword v127, v[8:9], off nt
	global_load_dword v128, v[10:11], off nt
	global_load_dword v129, v[12:13], off nt
	s_nop 0
	global_load_dword v14, v[14:15], off nt
	s_nop 0
	global_load_dword v15, v[16:17], off nt
	s_nop 0
	global_load_dword v16, v[18:19], off nt
	global_load_dword v17, v[20:21], off nt
	v_lshl_add_u64 v[6:7], v[4:5], 2, s[18:19]
	v_or_b32_e32 v4, s8, v71
	global_load_dword v18, v[6:7], off nt
	v_lshl_add_u64 v[6:7], v[4:5], 2, s[18:19]
	v_or_b32_e32 v4, s8, v72
	v_lshl_add_u64 v[8:9], v[4:5], 2, s[18:19]
	v_or_b32_e32 v4, s8, v73
	v_lshl_add_u64 v[10:11], v[4:5], 2, s[18:19]
	v_or_b32_e32 v4, s8, v74
	v_lshl_add_u64 v[12:13], v[4:5], 2, s[18:19]
	v_or_b32_e32 v4, s8, v78
	global_load_dword v19, v[6:7], off nt
	global_load_dword v20, v[8:9], off nt
	s_nop 0
	global_load_dword v10, v[10:11], off nt
	s_nop 0
	global_load_dword v11, v[12:13], off nt
	v_lshl_add_u64 v[6:7], v[4:5], 2, s[18:19]
	v_or_b32_e32 v4, s8, v79
	v_lshl_add_u64 v[8:9], v[4:5], 2, s[18:19]
	v_or_b32_e32 v4, s8, v80
	global_load_dword v12, v[6:7], off nt
	s_nop 0
	global_load_dword v8, v[8:9], off nt
	v_lshl_add_u64 v[6:7], v[4:5], 2, s[18:19]
	global_load_dword v4, v[6:7], off nt
	v_add_u32_e32 v7, v26, v34
	s_lshl_b64 s[18:19], s[8:9], 1
	s_add_u32 s4, s4, s18
	s_addc_u32 s5, s5, s19
	s_waitcnt vmcnt(31)
	v_mul_f32_e32 v6, v81, v110
	ds_write_b32 v27, v6
	s_waitcnt vmcnt(30)
	v_mul_f32_e32 v6, v82, v111
	s_waitcnt vmcnt(29)
	v_mul_f32_e32 v9, v83, v112
	ds_write2_b32 v7, v6, v9 offset1:66
	s_waitcnt vmcnt(28)
	v_mul_f32_e32 v6, v84, v113
	s_waitcnt vmcnt(27)
	v_mul_f32_e32 v9, v85, v114
	ds_write2_b32 v7, v6, v9 offset0:132 offset1:198
	s_waitcnt vmcnt(26)
	v_mul_f32_e32 v6, v87, v115
	s_waitcnt vmcnt(25)
	v_mul_f32_e32 v9, v88, v116
	v_add_u32_e32 v7, 0x400, v7
	ds_write2_b32 v7, v6, v9 offset0:8 offset1:74
	s_waitcnt vmcnt(24)
	v_mul_f32_e32 v6, v89, v117
	v_add_u32_e32 v9, 0x400, v75
	s_waitcnt vmcnt(23)
	v_mul_f32_e32 v7, v90, v118
	ds_write2_b32 v75, v6, v7 offset1:66
	s_waitcnt vmcnt(22)
	v_mul_f32_e32 v6, v91, v119
	s_waitcnt vmcnt(21)
	v_mul_f32_e32 v7, v92, v120
	ds_write2_b32 v75, v6, v7 offset0:132 offset1:198
	s_waitcnt vmcnt(20)
	v_mul_f32_e32 v6, v93, v121
	s_waitcnt vmcnt(19)
	v_mul_f32_e32 v7, v94, v122
	ds_write2_b32 v9, v6, v7 offset0:8 offset1:74
	s_waitcnt vmcnt(18)
	v_mul_f32_e32 v6, v95, v123
	s_waitcnt vmcnt(17)
	v_mul_f32_e32 v7, v96, v124
	ds_write2_b32 v76, v6, v7 offset1:66
	s_waitcnt vmcnt(16)
	v_mul_f32_e32 v6, v97, v125
	v_add_u32_e32 v9, 0x400, v76
	s_waitcnt vmcnt(15)
	v_mul_f32_e32 v7, v98, v126
	ds_write2_b32 v76, v6, v7 offset0:132 offset1:198
	s_waitcnt vmcnt(14)
	v_mul_f32_e32 v6, v99, v127
	s_waitcnt vmcnt(13)
	v_mul_f32_e32 v7, v100, v128
	ds_write2_b32 v9, v6, v7 offset0:8 offset1:74
	s_waitcnt vmcnt(12)
	v_mul_f32_e32 v6, v101, v129
	s_waitcnt vmcnt(11)
	v_mul_f32_e32 v7, v102, v14
	ds_write2_b32 v77, v6, v7 offset1:66
	s_waitcnt vmcnt(10)
	v_mul_f32_e32 v6, v103, v15
	s_waitcnt vmcnt(9)
	v_mul_f32_e32 v7, v104, v16
	ds_write2_b32 v77, v6, v7 offset0:132 offset1:198
	s_waitcnt vmcnt(8)
	v_mul_f32_e32 v6, v105, v17
	s_waitcnt vmcnt(7)
	v_mul_f32_e32 v7, v24, v18
	v_add_u32_e32 v9, 0x400, v77
	ds_write2_b32 v9, v6, v7 offset0:8 offset1:74
	v_add_u32_e32 v7, v26, v69
	s_waitcnt vmcnt(6)
	v_mul_f32_e32 v6, v25, v19
	s_waitcnt vmcnt(5)
	v_mul_f32_e32 v9, v106, v20
	ds_write2_b32 v7, v6, v9 offset0:66 offset1:132
	s_waitcnt vmcnt(4)
	v_mul_f32_e32 v6, v107, v10
	s_waitcnt vmcnt(3)
	v_mul_f32_e32 v9, v108, v11
	v_add_u32_e32 v10, 0x200, v7
	ds_write2_b32 v10, v6, v9 offset0:70 offset1:136
	s_waitcnt vmcnt(2)
	v_mul_f32_e32 v6, v109, v12
	s_waitcnt vmcnt(1)
	v_mul_f32_e32 v8, v22, v8
	v_add_u32_e32 v9, 0x400, v7
	s_waitcnt vmcnt(0)
	v_mul_f32_e32 v4, v23, v4
	ds_write2_b32 v9, v6, v8 offset0:74 offset1:140
	ds_write_b32 v7, v4 offset:1848
	s_waitcnt lgkmcnt(0)
	ds_read2_b32 v[6:7], v29 offset1:33
	v_lshlrev_b32_e32 v4, 1, v2
	s_waitcnt lgkmcnt(0)
	v_cvt_pk_bf16_f32 v6, v6, v7
	ds_read2_b32 v[8:9], v29 offset0:66 offset1:99
	v_lshl_add_u64 v[12:13], s[4:5], 0, v[4:5]
	v_or_b32_e32 v4, s20, v28
	s_waitcnt lgkmcnt(0)
	v_cvt_pk_bf16_f32 v7, v8, v9
	ds_read2_b32 v[8:9], v29 offset0:132 offset1:165
	v_lshl_add_u64 v[12:13], v[12:13], 0, s[10:11]
	v_lshlrev_b32_e32 v4, 11, v4
	s_waitcnt lgkmcnt(0)
	v_cvt_pk_bf16_f32 v8, v8, v9
	ds_read2_b32 v[10:11], v29 offset0:198 offset1:231
	s_waitcnt lgkmcnt(0)
	v_cvt_pk_bf16_f32 v9, v10, v11
	v_lshl_add_u64 v[14:15], v[12:13], 0, v[4:5]
	ds_read2_b32 v[10:11], v29 offset0:8 offset1:41
	global_store_dwordx4 v[14:15], v[6:9], off
	v_or_b32_e32 v4, s20, v30
	v_lshlrev_b32_e32 v4, 11, v4
	s_waitcnt lgkmcnt(0)
	v_cvt_pk_bf16_f32 v6, v10, v11
	ds_read2_b32 v[8:9], v29 offset0:74 offset1:107
	s_waitcnt lgkmcnt(0)
	v_cvt_pk_bf16_f32 v7, v8, v9
	ds_read2_b32 v[8:9], v29 offset0:140 offset1:173
	s_waitcnt lgkmcnt(0)
	v_cvt_pk_bf16_f32 v8, v8, v9
	ds_read2_b32 v[10:11], v29 offset0:206 offset1:239
	s_waitcnt lgkmcnt(0)
	v_cvt_pk_bf16_f32 v9, v10, v11
	v_lshl_add_u64 v[14:15], v[12:13], 0, v[4:5]
	ds_read2_b32 v[10:11], v29 offset0:16 offset1:49
	global_store_dwordx4 v[14:15], v[6:9], off
	v_or_b32_e32 v4, s20, v31
	v_lshlrev_b32_e32 v4, 11, v4
	s_waitcnt lgkmcnt(0)
	v_cvt_pk_bf16_f32 v6, v10, v11
	ds_read2_b32 v[8:9], v29 offset0:82 offset1:115
	s_waitcnt lgkmcnt(0)
	v_cvt_pk_bf16_f32 v7, v8, v9
	ds_read2_b32 v[8:9], v29 offset0:148 offset1:181
	s_waitcnt lgkmcnt(0)
	v_cvt_pk_bf16_f32 v8, v8, v9
	ds_read2_b32 v[10:11], v29 offset0:214 offset1:247
	s_waitcnt lgkmcnt(0)
	v_cvt_pk_bf16_f32 v9, v10, v11
	v_lshl_add_u64 v[14:15], v[12:13], 0, v[4:5]
	ds_read2_b32 v[10:11], v29 offset0:24 offset1:57
	global_store_dwordx4 v[14:15], v[6:9], off
	v_or_b32_e32 v4, s20, v32
	v_lshlrev_b32_e32 v4, 11, v4
	s_waitcnt lgkmcnt(0)
	v_cvt_pk_bf16_f32 v6, v10, v11
	ds_read2_b32 v[8:9], v29 offset0:90 offset1:123
	s_waitcnt lgkmcnt(0)
	v_cvt_pk_bf16_f32 v7, v8, v9
	ds_read2_b32 v[8:9], v29 offset0:156 offset1:189
	s_waitcnt lgkmcnt(0)
	v_cvt_pk_bf16_f32 v8, v8, v9
	ds_read2_b32 v[10:11], v29 offset0:222 offset1:255
	s_waitcnt lgkmcnt(0)
	v_cvt_pk_bf16_f32 v9, v10, v11
	v_lshl_add_u64 v[10:11], v[12:13], 0, v[4:5]
	global_store_dwordx4 v[10:11], v[6:9], off
	s_waitcnt lgkmcnt(0)

.LBB0_62:
	s_andn2_b64 vcc, exec, s[4:5]
	s_cbranch_vccnz .LBB0_88
	v_mov_b32_e32 v4, s0
	v_mov_b32_e32 v6, s1
	s_and_b32 s8, s29, 0x1fc0
	v_readfirstlane_b32 s4, v4
	v_readfirstlane_b32 s5, v6
	s_load_dwordx2 s[4:5], s[4:5], 0x88
	s_and_b32 s72, s27, 0x1e0
	s_addk_i32 s8, 0xe880
	s_lshl_b32 s18, s72, 2
	v_or_b32_e32 v81, s8, v3
	s_waitcnt lgkmcnt(0)
	s_add_u32 s4, s4, s18
	s_addc_u32 s5, s5, 0
	v_lshlrev_b32_e32 v4, 2, v0
	v_lshl_add_u64 v[6:7], s[4:5], 0, v[4:5]
	v_mov_b32_e32 v4, v81
	v_or_b32_e32 v18, 10, v81
	v_mov_b32_e32 v19, v5
	v_or_b32_e32 v20, 12, v81
	v_mov_b32_e32 v21, v5
	v_lshlrev_b64 v[8:9], 11, v[4:5]
	v_or_b32_e32 v10, 2, v81
	v_mov_b32_e32 v11, v5
	v_or_b32_e32 v12, 4, v81
	v_mov_b32_e32 v13, v5
	v_or_b32_e32 v14, 6, v81
	v_mov_b32_e32 v15, v5
	v_or_b32_e32 v16, 8, v81
	v_mov_b32_e32 v17, v5
	v_lshlrev_b64 v[18:19], 11, v[18:19]
	v_lshlrev_b64 v[20:21], 11, v[20:21]
	v_or_b32_e32 v22, 14, v81
	v_mov_b32_e32 v23, v5
	v_mov_b32_e32 v108, s0
	v_mov_b32_e32 v109, s1
	v_mov_b32_e32 v110, s0
	v_mov_b32_e32 v111, s1
	v_lshl_add_u64 v[8:9], v[6:7], 0, v[8:9]
	v_lshlrev_b64 v[10:11], 11, v[10:11]
	v_lshlrev_b64 v[12:13], 11, v[12:13]
	v_lshlrev_b64 v[14:15], 11, v[14:15]
	v_lshlrev_b64 v[16:17], 11, v[16:17]
	v_lshl_add_u64 v[18:19], v[6:7], 0, v[18:19]
	v_lshl_add_u64 v[20:21], v[6:7], 0, v[20:21]
	v_lshlrev_b64 v[22:23], 11, v[22:23]
	v_lshl_add_u64 v[10:11], v[6:7], 0, v[10:11]
	v_lshl_add_u64 v[12:13], v[6:7], 0, v[12:13]
	v_lshl_add_u64 v[14:15], v[6:7], 0, v[14:15]
	v_lshl_add_u64 v[16:17], v[6:7], 0, v[16:17]
	v_lshl_add_u64 v[24:25], v[6:7], 0, v[22:23]
	global_load_dword v97, v[8:9], off nt
	global_load_dword v96, v[10:11], off nt
	global_load_dword v22, v[12:13], off nt
	global_load_dword v23, v[14:15], off nt
	global_load_dword v94, v[16:17], off nt
	global_load_dword v95, v[18:19], off nt
	s_nop 0
	global_load_dword v20, v[20:21], off nt
	s_nop 0
	global_load_dword v21, v[24:25], off nt
	v_or_b32_e32 v18, 26, v81
	v_mov_b32_e32 v19, v5
	v_lshlrev_b64 v[18:19], 11, v[18:19]
	v_lshl_add_u64 v[24:25], v[6:7], 0, v[18:19]
	v_or_b32_e32 v18, 28, v81
	v_mov_b32_e32 v19, v5
	v_or_b32_e32 v8, 16, v81
	v_mov_b32_e32 v9, v5
	v_or_b32_e32 v14, 22, v81
	v_mov_b32_e32 v15, v5
	v_or_b32_e32 v16, 24, v81
	v_mov_b32_e32 v17, v5
	v_lshlrev_b64 v[18:19], 11, v[18:19]
	v_lshlrev_b64 v[8:9], 11, v[8:9]
	v_or_b32_e32 v10, 18, v81
	v_mov_b32_e32 v11, v5
	v_or_b32_e32 v12, 20, v81
	v_mov_b32_e32 v13, v5
	v_lshlrev_b64 v[14:15], 11, v[14:15]
	v_lshlrev_b64 v[16:17], 11, v[16:17]
	v_lshl_add_u64 v[82:83], v[6:7], 0, v[18:19]
	v_or_b32_e32 v18, 30, v81
	v_mov_b32_e32 v19, v5
	v_lshl_add_u64 v[8:9], v[6:7], 0, v[8:9]
	v_lshlrev_b64 v[10:11], 11, v[10:11]
	v_lshlrev_b64 v[12:13], 11, v[12:13]
	v_lshl_add_u64 v[14:15], v[6:7], 0, v[14:15]
	v_lshl_add_u64 v[16:17], v[6:7], 0, v[16:17]
	v_lshlrev_b64 v[18:19], 11, v[18:19]
	v_lshl_add_u64 v[10:11], v[6:7], 0, v[10:11]
	v_lshl_add_u64 v[12:13], v[6:7], 0, v[12:13]
	v_lshl_add_u64 v[84:85], v[6:7], 0, v[18:19]
	global_load_dword v92, v[8:9], off nt
	global_load_dword v93, v[10:11], off nt
	global_load_dword v18, v[12:13], off nt
	global_load_dword v19, v[14:15], off nt
	global_load_dword v90, v[16:17], off nt
	global_load_dword v91, v[24:25], off nt
	s_nop 0
	global_load_dword v16, v[82:83], off nt
	global_load_dword v17, v[84:85], off nt
	v_or_b32_e32 v14, 38, v81
	v_mov_b32_e32 v15, v5
	v_lshlrev_b64 v[14:15], 11, v[14:15]
	v_lshl_add_u64 v[24:25], v[6:7], 0, v[14:15]
	v_or_b32_e32 v14, 40, v81
	v_mov_b32_e32 v15, v5
	v_lshlrev_b64 v[14:15], 11, v[14:15]
	v_lshl_add_u64 v[82:83], v[6:7], 0, v[14:15]
	v_or_b32_e32 v14, 42, v81
	v_mov_b32_e32 v15, v5
	v_lshlrev_b64 v[14:15], 11, v[14:15]
	v_lshl_add_u64 v[98:99], v[6:7], 0, v[14:15]
	v_or_b32_e32 v14, 44, v81
	v_mov_b32_e32 v15, v5
	v_or_b32_e32 v8, 32, v81
	v_mov_b32_e32 v9, v5
	v_or_b32_e32 v12, 36, v81
	v_mov_b32_e32 v13, v5
	v_lshlrev_b64 v[14:15], 11, v[14:15]
	v_lshlrev_b64 v[8:9], 11, v[8:9]
	v_or_b32_e32 v10, 34, v81
	v_mov_b32_e32 v11, v5
	v_lshlrev_b64 v[12:13], 11, v[12:13]
	v_lshl_add_u64 v[100:101], v[6:7], 0, v[14:15]
	v_or_b32_e32 v14, 46, v81
	v_mov_b32_e32 v15, v5
	v_lshl_add_u64 v[8:9], v[6:7], 0, v[8:9]
	v_lshlrev_b64 v[10:11], 11, v[10:11]
	v_lshl_add_u64 v[12:13], v[6:7], 0, v[12:13]
	v_lshlrev_b64 v[14:15], 11, v[14:15]
	v_lshl_add_u64 v[10:11], v[6:7], 0, v[10:11]
	v_lshl_add_u64 v[102:103], v[6:7], 0, v[14:15]
	global_load_dword v88, v[8:9], off nt
	global_load_dword v89, v[10:11], off nt
	global_load_dword v14, v[12:13], off nt
	global_load_dword v15, v[24:25], off nt
	global_load_dword v85, v[82:83], off nt
	global_load_dword v87, v[98:99], off nt
	s_nop 0
	global_load_dword v12, v[100:101], off nt
	global_load_dword v13, v[102:103], off nt
	v_or_b32_e32 v82, 54, v81
	v_mov_b32_e32 v83, v5
	v_lshlrev_b64 v[82:83], 11, v[82:83]
	v_lshl_add_u64 v[98:99], v[6:7], 0, v[82:83]
	v_or_b32_e32 v82, 56, v81
	v_mov_b32_e32 v83, v5
	v_lshlrev_b64 v[82:83], 11, v[82:83]
	v_lshl_add_u64 v[100:101], v[6:7], 0, v[82:83]
	v_or_b32_e32 v82, 58, v81
	v_mov_b32_e32 v83, v5
	v_lshlrev_b64 v[82:83], 11, v[82:83]
	v_lshl_add_u64 v[102:103], v[6:7], 0, v[82:83]
	v_or_b32_e32 v82, 60, v81
	v_mov_b32_e32 v83, v5
	v_or_b32_e32 v8, 48, v81
	v_mov_b32_e32 v9, v5
	v_or_b32_e32 v10, 50, v81
	v_mov_b32_e32 v11, v5
	v_lshlrev_b64 v[82:83], 11, v[82:83]
	v_lshlrev_b64 v[8:9], 11, v[8:9]
	v_lshlrev_b64 v[10:11], 11, v[10:11]
	v_or_b32_e32 v24, 52, v81
	v_mov_b32_e32 v25, v5
	v_lshl_add_u64 v[104:105], v[6:7], 0, v[82:83]
	v_or_b32_e32 v82, 62, v81
	v_mov_b32_e32 v83, v5
	v_lshl_add_u64 v[8:9], v[6:7], 0, v[8:9]
	v_lshl_add_u64 v[10:11], v[6:7], 0, v[10:11]
	v_lshlrev_b64 v[24:25], 11, v[24:25]
	v_lshlrev_b64 v[82:83], 11, v[82:83]
	v_lshl_add_u64 v[24:25], v[6:7], 0, v[24:25]
	v_lshl_add_u64 v[106:107], v[6:7], 0, v[82:83]
	global_load_dword v83, v[8:9], off nt
	global_load_dword v84, v[10:11], off nt
	s_nop 0
	global_load_dword v10, v[24:25], off nt
	global_load_dword v11, v[98:99], off nt
	global_load_dword v81, v[100:101], off nt
	global_load_dword v82, v[102:103], off nt
	global_load_dword v6, v[104:105], off nt
	global_load_dword v7, v[106:107], off nt
	v_readfirstlane_b32 s4, v108
	v_readfirstlane_b32 s5, v109
	s_load_dwordx2 s[20:21], s[4:5], 0x80
	v_readfirstlane_b32 s4, v110
	v_readfirstlane_b32 s5, v111
	v_add_u32_e32 v8, s8, v3
	s_waitcnt lgkmcnt(0)
	s_cmp_lg_u64 s[20:21], 0
	s_cselect_b64 s[22:23], -1, 0
	s_cmp_eq_u64 s[20:21], 0
	s_cbranch_scc1 .LBB0_133
	v_lshl_add_u64 v[24:25], v[4:5], 2, s[20:21]
	v_mov_b32_e32 v9, v5
	v_lshl_add_u64 v[98:99], v[8:9], 2, s[20:21]
	global_load_dword v4, v[24:25], off nt
	global_load_dword v9, v[98:99], off offset:8 nt
	s_nop 0
	global_load_dword v24, v[98:99], off offset:16 nt
	global_load_dword v25, v[98:99], off offset:24 nt
	v_add_u32_e32 v98, v26, v34
	s_waitcnt vmcnt(3)
	v_mul_f32_e32 v4, v97, v4
	s_waitcnt vmcnt(2)
	v_mul_f32_e32 v9, v96, v9
	ds_write_b32 v27, v4
	s_waitcnt vmcnt(0)
	v_pk_mul_f32 v[24:25], v[22:23], v[24:25]
	ds_write_b32 v98, v9
	s_load_dwordx2 s[18:19], s[4:5], 0xc0
	s_cbranch_execnz .LBB0_66

.LBB0_66:
	v_cndmask_b32_e64 v9, 0, 1, s[22:23]
	v_add_u32_e32 v4, v26, v36
	v_cmp_ne_u32_e64 s[4:5], 1, v9
	s_andn2_b64 vcc, exec, s[22:23]
	ds_write2_b32 v4, v24, v25 offset1:66
	s_cbranch_vccnz .LBB0_134
	v_mov_b32_e32 v9, v5
	s_waitcnt vmcnt(28)
	v_lshl_add_u64 v[22:23], v[8:9], 2, s[20:21]
	global_load_dword v4, v[22:23], off offset:32 nt
	global_load_dword v9, v[22:23], off offset:40 nt
	global_load_dword v24, v[22:23], off offset:48 nt
	global_load_dword v25, v[22:23], off offset:56 nt
	v_add_u32_e32 v96, v26, v39
	s_waitcnt vmcnt(3)
	v_mul_f32_e32 v4, v94, v4
	s_waitcnt vmcnt(2)
	v_mul_f32_e32 v9, v95, v9
	ds_write2_b32 v96, v4, v9 offset1:66
	s_waitcnt vmcnt(0)
	v_pk_mul_f32 v[22:23], v[20:21], v[24:25]
	s_cbranch_execnz .LBB0_69

.LBB0_69:
	v_add_u32_e32 v4, v26, v42
	s_and_b64 vcc, exec, s[4:5]
	s_waitcnt vmcnt(28)
	ds_write2_b32 v4, v22, v23 offset1:66
	s_cbranch_vccnz .LBB0_135
	v_mov_b32_e32 v9, v5
	s_waitcnt vmcnt(24)
	v_lshl_add_u64 v[20:21], v[8:9], 2, s[20:21]
	global_load_dword v4, v[20:21], off offset:64 nt
	global_load_dword v9, v[20:21], off offset:72 nt
	global_load_dword v22, v[20:21], off offset:80 nt
	global_load_dword v23, v[20:21], off offset:88 nt
	v_add_u32_e32 v24, v26, v45
	s_waitcnt vmcnt(3)
	v_mul_f32_e32 v4, v92, v4
	s_waitcnt vmcnt(2)
	v_mul_f32_e32 v9, v93, v9
	ds_write2_b32 v24, v4, v9 offset1:66
	s_waitcnt vmcnt(0)
	v_pk_mul_f32 v[20:21], v[18:19], v[22:23]
	s_cbranch_execnz .LBB0_72

.LBB0_72:
	v_add_u32_e32 v4, v26, v48
	s_and_b64 vcc, exec, s[4:5]
	s_waitcnt vmcnt(24)
	ds_write2_b32 v4, v20, v21 offset1:66
	s_cbranch_vccnz .LBB0_136
	v_mov_b32_e32 v9, v5
	s_waitcnt vmcnt(20)
	v_lshl_add_u64 v[18:19], v[8:9], 2, s[20:21]
	global_load_dword v4, v[18:19], off offset:96 nt
	global_load_dword v9, v[18:19], off offset:104 nt
	global_load_dword v20, v[18:19], off offset:112 nt
	global_load_dword v21, v[18:19], off offset:120 nt
	v_add_u32_e32 v22, v26, v51
	s_waitcnt vmcnt(3)
	v_mul_f32_e32 v4, v90, v4
	s_waitcnt vmcnt(2)
	v_mul_f32_e32 v9, v91, v9
	ds_write2_b32 v22, v4, v9 offset1:66
	s_waitcnt vmcnt(0)
	v_pk_mul_f32 v[18:19], v[16:17], v[20:21]
	s_cbranch_execnz .LBB0_75

.LBB0_75:
	v_add_u32_e32 v4, v26, v54
	s_and_b64 vcc, exec, s[4:5]
	s_waitcnt vmcnt(20)
	ds_write2_b32 v4, v18, v19 offset1:66
	s_cbranch_vccnz .LBB0_137
	v_mov_b32_e32 v9, v5
	s_waitcnt vmcnt(16)
	v_lshl_add_u64 v[16:17], v[8:9], 2, s[20:21]
	global_load_dword v4, v[16:17], off offset:128 nt
	global_load_dword v9, v[16:17], off offset:136 nt
	global_load_dword v18, v[16:17], off offset:144 nt
	global_load_dword v19, v[16:17], off offset:152 nt
	v_add_u32_e32 v20, v26, v57
	s_waitcnt vmcnt(3)
	v_mul_f32_e32 v4, v88, v4
	s_waitcnt vmcnt(2)
	v_mul_f32_e32 v9, v89, v9
	ds_write2_b32 v20, v4, v9 offset1:66
	s_waitcnt vmcnt(0)
	v_pk_mul_f32 v[16:17], v[14:15], v[18:19]
	s_cbranch_execnz .LBB0_78

.LBB0_78:
	v_add_u32_e32 v4, v26, v60
	s_and_b64 vcc, exec, s[4:5]
	s_waitcnt vmcnt(16)
	ds_write2_b32 v4, v16, v17 offset1:66
	s_cbranch_vccnz .LBB0_138
	v_mov_b32_e32 v9, v5
	s_waitcnt vmcnt(12)
	v_lshl_add_u64 v[14:15], v[8:9], 2, s[20:21]
	global_load_dword v4, v[14:15], off offset:160 nt
	global_load_dword v9, v[14:15], off offset:168 nt
	global_load_dword v16, v[14:15], off offset:176 nt
	global_load_dword v17, v[14:15], off offset:184 nt
	v_add_u32_e32 v18, v26, v63
	s_waitcnt vmcnt(3)
	v_mul_f32_e32 v4, v85, v4
	s_waitcnt vmcnt(2)
	v_mul_f32_e32 v9, v87, v9
	ds_write2_b32 v18, v4, v9 offset1:66
	s_waitcnt vmcnt(0)
	v_pk_mul_f32 v[14:15], v[12:13], v[16:17]
	s_cbranch_execnz .LBB0_81

.LBB0_81:
	v_add_u32_e32 v4, v26, v66
	s_and_b64 vcc, exec, s[4:5]
	s_waitcnt vmcnt(12)
	ds_write2_b32 v4, v14, v15 offset1:66
	s_cbranch_vccnz .LBB0_139
	v_mov_b32_e32 v9, v5
	s_waitcnt vmcnt(8)
	v_lshl_add_u64 v[12:13], v[8:9], 2, s[20:21]
	global_load_dword v4, v[12:13], off offset:192 nt
	global_load_dword v9, v[12:13], off offset:200 nt
	global_load_dword v14, v[12:13], off offset:208 nt
	global_load_dword v15, v[12:13], off offset:216 nt
	v_add_u32_e32 v16, v26, v69
	s_waitcnt vmcnt(3)
	v_mul_f32_e32 v4, v83, v4
	s_waitcnt vmcnt(2)
	v_mul_f32_e32 v9, v84, v9
	ds_write2_b32 v16, v4, v9 offset1:66
	s_waitcnt vmcnt(0)
	v_pk_mul_f32 v[12:13], v[10:11], v[14:15]
	s_cbranch_execnz .LBB0_84

.LBB0_84:
	v_add_u32_e32 v4, v26, v69
	s_waitcnt vmcnt(8)
	ds_write2_b32 v4, v12, v13 offset0:132 offset1:198
	s_and_b64 vcc, exec, s[4:5]
	v_add_u32_e32 v4, 0x400, v4
	s_cbranch_vccnz .LBB0_140
	v_mov_b32_e32 v9, v5
	v_lshl_add_u64 v[8:9], v[8:9], 2, s[20:21]
	global_load_dword v12, v[8:9], off offset:224 nt
	global_load_dword v13, v[8:9], off offset:232 nt
	global_load_dword v10, v[8:9], off offset:240 nt
	global_load_dword v11, v[8:9], off offset:248 nt
	s_waitcnt vmcnt(3)
	v_mul_f32_e32 v12, v81, v12
	s_waitcnt vmcnt(2)
	v_mul_f32_e32 v13, v82, v13
	ds_write2_b32 v4, v12, v13 offset0:8 offset1:74
	s_waitcnt vmcnt(0)
	v_pk_mul_f32 v[8:9], v[6:7], v[10:11]
	s_cbranch_execnz .LBB0_87

.LBB0_94:
	s_lshr_b32 s8, s20, 3
	s_add_i32 s23, s8, -6
	s_and_b64 s[4:5], exec, s[4:5]
	s_cselect_b32 s8, s8, s23
	s_add_u32 s4, s21, s18
	s_addc_u32 s5, s22, s19
	s_load_dwordx2 s[4:5], s[4:5], 0x0
	v_mov_b32_e32 v4, s0
	v_mov_b32_e32 v6, s1
	s_lshl_b64 s[18:19], s[8:9], 16
	v_readfirstlane_b32 s22, v4
	v_readfirstlane_b32 s23, v6
	s_load_dwordx2 s[22:23], s[22:23], 0xc0
	s_waitcnt lgkmcnt(0)
	s_add_u32 s8, s4, s18
	s_addc_u32 s5, s5, s19
	s_and_b32 s21, s31, 64
	s_and_b32 s24, s27, 0x60
	s_add_u32 s22, s22, s18
	s_addc_u32 s23, s23, s19
	s_cmp_gt_u32 s20, 47
	s_cselect_b32 s4, 0x80, 0
	s_or_b32 s4, s4, s24
	s_lshl_b32 s18, s24, 2
	s_add_u32 s18, s8, s18
	v_or_b32_e32 v8, s21, v3
	s_addc_u32 s19, s5, 0
	v_lshlrev_b32_e32 v4, 2, v0
	v_lshl_add_u64 v[6:7], s[18:19], 0, v[4:5]
	v_lshlrev_b32_e32 v4, 9, v8
	v_lshl_add_u64 v[6:7], v[6:7], 0, v[4:5]
	s_movk_i32 s5, 0x1000
	v_add_co_u32_e32 v8, vcc, s5, v6
	v_add_u32_e32 v94, 0x800, v27
	s_nop 0
	v_addc_co_u32_e32 v9, vcc, 0, v7, vcc
	v_add_co_u32_e32 v10, vcc, s35, v6
	v_add_u32_e32 v95, 0xc00, v27
	s_nop 0
	v_addc_co_u32_e32 v11, vcc, 0, v7, vcc
	v_add_co_u32_e32 v12, vcc, s67, v6
	v_add_u32_e32 v96, 0x1000, v27
	s_nop 0
	v_addc_co_u32_e32 v13, vcc, 0, v7, vcc
	v_add_co_u32_e32 v14, vcc, s36, v6
	s_lshl_b32 s5, s21, 1
	s_nop 0
	v_addc_co_u32_e32 v15, vcc, 0, v7, vcc
	global_load_dword v4, v[6:7], off nt
	global_load_dword v16, v[6:7], off offset:1024 nt
	global_load_dword v17, v[6:7], off offset:2048 nt
	global_load_dword v18, v[6:7], off offset:3072 nt
	global_load_dword v19, v[8:9], off offset:1024 nt
	global_load_dword v20, v[8:9], off offset:2048 nt
	global_load_dword v21, v[8:9], off offset:3072 nt
	global_load_dword v22, v[12:13], off offset:1024 nt
	global_load_dword v23, v[10:11], off offset:-4096 nt
	global_load_dword v24, v[10:11], off nt
	global_load_dword v25, v[10:11], off offset:1024 nt
	global_load_dword v81, v[10:11], off offset:2048 nt
	global_load_dword v82, v[10:11], off offset:3072 nt
	global_load_dword v83, v[14:15], off offset:-4096 nt
	global_load_dword v84, v[14:15], off nt
	v_add_co_u32_e32 v8, vcc, s68, v6
	s_add_u32 s18, s22, s5
	s_nop 0
	v_addc_co_u32_e32 v9, vcc, 0, v7, vcc
	v_add_co_u32_e32 v10, vcc, s37, v6
	s_addc_u32 s19, s23, 0
	s_nop 0
	v_addc_co_u32_e32 v11, vcc, 0, v7, vcc
	v_add_co_u32_e32 v6, vcc, s69, v6
	global_load_dword v85, v[12:13], off offset:2048 nt
	s_nop 0
	global_load_dword v12, v[12:13], off offset:3072 nt
	s_nop 0
	global_load_dword v13, v[8:9], off offset:1024 nt
	global_load_dword v87, v[8:9], off offset:2048 nt
	s_nop 0
	global_load_dword v8, v[8:9], off offset:3072 nt
	s_nop 0
	global_load_dword v9, v[14:15], off offset:1024 nt
	global_load_dword v88, v[14:15], off offset:2048 nt
	s_nop 0
	global_load_dword v14, v[14:15], off offset:3072 nt
	s_nop 0
	global_load_dword v15, v[10:11], off offset:-4096 nt
	global_load_dword v89, v[10:11], off nt
	global_load_dword v90, v[10:11], off offset:1024 nt
	global_load_dword v91, v[10:11], off offset:2048 nt
	s_nop 0
	global_load_dword v10, v[10:11], off offset:3072 nt
	v_addc_co_u32_e32 v7, vcc, 0, v7, vcc
	global_load_dword v11, v[6:7], off nt
	global_load_dword v92, v[6:7], off offset:1024 nt
	global_load_dword v93, v[6:7], off offset:2048 nt
	s_nop 0
	global_load_dword v6, v[6:7], off offset:3072 nt
	v_add_u32_e32 v7, 0x400, v27
	s_waitcnt vmcnt(30)
	ds_write2_b32 v27, v4, v16 offset1:66
	s_waitcnt vmcnt(28)
	ds_write2_b32 v27, v17, v18 offset0:132 offset1:198
	s_waitcnt vmcnt(23)
	ds_write2_b32 v7, v23, v19 offset0:8 offset1:74
	ds_write2_b32 v7, v20, v21 offset0:140 offset1:206
	s_waitcnt vmcnt(21)
	ds_write2_b32 v94, v24, v25 offset0:16 offset1:82
	s_waitcnt vmcnt(19)
	ds_write2_b32 v94, v81, v82 offset0:148 offset1:214
	s_waitcnt vmcnt(18)
	ds_write2_b32 v95, v83, v22 offset0:24 offset1:90
	s_waitcnt vmcnt(15)
	ds_write2_b32 v95, v85, v12 offset0:156 offset1:222
	s_waitcnt vmcnt(11)
	ds_write2_b32 v96, v84, v9 offset0:32 offset1:98
	s_waitcnt vmcnt(9)
	ds_write2_b32 v96, v88, v14 offset0:164 offset1:230
	v_add_u32_e32 v4, 0x1400, v27
	s_waitcnt vmcnt(8)
	ds_write2_b32 v4, v15, v13 offset0:40 offset1:106
	ds_write2_b32 v4, v87, v8 offset0:172 offset1:238
	v_add_u32_e32 v4, 0x1800, v27
	s_waitcnt vmcnt(6)
	ds_write2_b32 v4, v89, v90 offset0:48 offset1:114
	s_waitcnt vmcnt(4)
	ds_write2_b32 v4, v91, v10 offset0:180 offset1:246
	v_add_u32_e32 v4, 0x1c00, v27
	s_waitcnt vmcnt(2)
	ds_write2_b32 v4, v11, v92 offset0:56 offset1:122
	s_waitcnt vmcnt(0)
	ds_write2_b32 v4, v93, v6 offset0:188 offset1:254
	s_waitcnt lgkmcnt(0)
	ds_read2_b32 v[6:7], v29 offset1:33
	v_lshlrev_b32_e32 v4, 1, v2
	s_waitcnt lgkmcnt(0)
	v_cvt_pk_bf16_f32 v6, v6, v7
	ds_read2_b32 v[8:9], v29 offset0:66 offset1:99
	v_lshl_add_u64 v[12:13], s[18:19], 0, v[4:5]
	v_or_b32_e32 v4, s4, v28
	s_waitcnt lgkmcnt(0)
	v_cvt_pk_bf16_f32 v7, v8, v9
	ds_read2_b32 v[8:9], v29 offset0:132 offset1:165
	v_lshl_add_u64 v[12:13], v[12:13], 0, s[12:13]
	v_lshlrev_b32_e32 v4, 8, v4
	s_waitcnt lgkmcnt(0)
	v_cvt_pk_bf16_f32 v8, v8, v9
	ds_read2_b32 v[10:11], v29 offset0:198 offset1:231
	s_waitcnt lgkmcnt(0)
	v_cvt_pk_bf16_f32 v9, v10, v11
	v_lshl_add_u64 v[14:15], v[12:13], 0, v[4:5]
	ds_read2_b32 v[10:11], v29 offset0:8 offset1:41
	global_store_dwordx4 v[14:15], v[6:9], off
	v_or_b32_e32 v4, s4, v30
	v_lshlrev_b32_e32 v4, 8, v4
	s_waitcnt lgkmcnt(0)
	v_cvt_pk_bf16_f32 v6, v10, v11
	ds_read2_b32 v[8:9], v29 offset0:74 offset1:107
	s_waitcnt lgkmcnt(0)
	v_cvt_pk_bf16_f32 v7, v8, v9
	ds_read2_b32 v[8:9], v29 offset0:140 offset1:173
	s_waitcnt lgkmcnt(0)
	v_cvt_pk_bf16_f32 v8, v8, v9
	ds_read2_b32 v[10:11], v29 offset0:206 offset1:239
	s_waitcnt lgkmcnt(0)
	v_cvt_pk_bf16_f32 v9, v10, v11
	v_lshl_add_u64 v[14:15], v[12:13], 0, v[4:5]
	ds_read2_b32 v[10:11], v29 offset0:16 offset1:49
	global_store_dwordx4 v[14:15], v[6:9], off
	v_or_b32_e32 v4, s4, v31
	v_lshlrev_b32_e32 v4, 8, v4
	s_waitcnt lgkmcnt(0)
	v_cvt_pk_bf16_f32 v6, v10, v11
	ds_read2_b32 v[8:9], v29 offset0:82 offset1:115
	s_waitcnt lgkmcnt(0)
	v_cvt_pk_bf16_f32 v7, v8, v9
	ds_read2_b32 v[8:9], v29 offset0:148 offset1:181
	s_waitcnt lgkmcnt(0)
	v_cvt_pk_bf16_f32 v8, v8, v9
	ds_read2_b32 v[10:11], v29 offset0:214 offset1:247
	s_waitcnt lgkmcnt(0)
	v_cvt_pk_bf16_f32 v9, v10, v11
	v_lshl_add_u64 v[14:15], v[12:13], 0, v[4:5]
	ds_read2_b32 v[10:11], v29 offset0:24 offset1:57
	global_store_dwordx4 v[14:15], v[6:9], off
	v_or_b32_e32 v4, s4, v32
	v_lshlrev_b32_e32 v4, 8, v4
	s_waitcnt lgkmcnt(0)
	v_cvt_pk_bf16_f32 v6, v10, v11
	ds_read2_b32 v[8:9], v29 offset0:90 offset1:123
	s_waitcnt lgkmcnt(0)
	v_cvt_pk_bf16_f32 v7, v8, v9
	ds_read2_b32 v[8:9], v29 offset0:156 offset1:189
	s_waitcnt lgkmcnt(0)
	v_cvt_pk_bf16_f32 v8, v8, v9
	ds_read2_b32 v[10:11], v29 offset0:222 offset1:255
	s_waitcnt lgkmcnt(0)
	v_cvt_pk_bf16_f32 v9, v10, v11
	v_lshl_add_u64 v[10:11], v[12:13], 0, v[4:5]
	global_store_dwordx4 v[10:11], v[6:9], off
	s_waitcnt lgkmcnt(0)

.LBB0_96:
	s_andn2_b64 vcc, exec, s[4:5]
	s_cbranch_vccnz .LBB0_122
	s_add_i32 s4, s38, 0xfe00
	s_bfe_u32 s5, s4, 0xd0003
	s_mulk_i32 s5, 0x2493
	s_lshr_b32 s18, s5, 16
	s_mul_i32 s5, s18, 56
	v_mov_b32_e32 v4, s0
	v_mov_b32_e32 v6, s1
	s_sub_i32 s8, s4, s5
	s_lshl_b32 s72, s18, 6
	v_readfirstlane_b32 s4, v4
	v_readfirstlane_b32 s5, v6
	s_load_dwordx2 s[4:5], s[4:5], 0x40
	s_lshl_b32 s18, s8, 7
	s_and_b32 s18, s18, 0x3ff80
	v_or_b32_e32 v22, s72, v3
	v_lshlrev_b32_e32 v4, 2, v0
	s_waitcnt lgkmcnt(0)
	s_add_u32 s4, s4, s18
	s_addc_u32 s5, s5, 0
	v_lshl_add_u64 v[6:7], s[4:5], 0, v[4:5]
	v_mul_u32_u24_e32 v4, 0x700, v22
	v_mad_u64_u32 v[8:9], s[4:5], v22, s70, v[6:7]
	v_lshl_add_u64 v[6:7], v[4:5], 2, v[6:7]
	v_add_co_u32_e32 v10, vcc, s67, v6
	v_mov_b32_e32 v23, s0
	s_nop 0
	v_addc_co_u32_e32 v11, vcc, 0, v7, vcc
	v_add_co_u32_e32 v12, vcc, s69, v6
	v_mov_b32_e32 v81, s1
	s_nop 0
	v_addc_co_u32_e32 v13, vcc, 0, v7, vcc
	v_add_co_u32_e32 v14, vcc, s39, v6
	v_mov_b32_e32 v110, s0
	s_nop 0
	v_addc_co_u32_e32 v15, vcc, 0, v7, vcc
	v_add_co_u32_e32 v16, vcc, s41, v6
	v_mov_b32_e32 v111, s1
	s_nop 0
	v_addc_co_u32_e32 v17, vcc, 0, v7, vcc
	v_add_co_u32_e32 v18, vcc, s71, v6
	s_nop 1
	v_addc_co_u32_e32 v19, vcc, 0, v7, vcc
	v_add_co_u32_e32 v24, vcc, s80, v6
	v_readfirstlane_b32 s4, v23
	s_nop 0
	v_addc_co_u32_e32 v25, vcc, 0, v7, vcc
	v_add_co_u32_e32 v82, vcc, s46, v6
	v_readfirstlane_b32 s5, v81
	s_nop 0
	v_addc_co_u32_e32 v83, vcc, 0, v7, vcc
	global_load_dword v94, v[8:9], off nt
	global_load_dword v95, v[10:11], off offset:2048 nt
	global_load_dword v20, v[12:13], off nt
	global_load_dword v21, v[14:15], off offset:2048 nt
	global_load_dword v92, v[16:17], off nt
	global_load_dword v93, v[18:19], off offset:2048 nt
	s_nop 0
	global_load_dword v18, v[24:25], off nt
	global_load_dword v19, v[82:83], off offset:2048 nt
	v_add_co_u32_e32 v8, vcc, s48, v6
	v_add_lshl_u32 v81, s72, v3, 2
	s_nop 0
	v_addc_co_u32_e32 v9, vcc, 0, v7, vcc
	v_add_co_u32_e32 v10, vcc, s81, v6
	s_nop 1
	v_addc_co_u32_e32 v11, vcc, 0, v7, vcc
	v_add_co_u32_e32 v12, vcc, s82, v6
	s_nop 1
	v_addc_co_u32_e32 v13, vcc, 0, v7, vcc
	v_add_co_u32_e32 v14, vcc, s53, v6
	s_nop 1
	v_addc_co_u32_e32 v15, vcc, 0, v7, vcc
	v_add_co_u32_e32 v24, vcc, s55, v6
	s_nop 1
	v_addc_co_u32_e32 v25, vcc, 0, v7, vcc
	v_add_co_u32_e32 v82, vcc, s83, v6
	s_nop 1
	v_addc_co_u32_e32 v83, vcc, 0, v7, vcc
	v_add_co_u32_e32 v84, vcc, s84, v6
	s_nop 1
	v_addc_co_u32_e32 v85, vcc, 0, v7, vcc
	v_add_co_u32_e32 v96, vcc, s60, v6
	s_nop 1
	v_addc_co_u32_e32 v97, vcc, 0, v7, vcc
	global_load_dword v90, v[8:9], off nt
	global_load_dword v91, v[10:11], off offset:2048 nt
	global_load_dword v16, v[12:13], off nt
	global_load_dword v17, v[14:15], off offset:2048 nt
	global_load_dword v88, v[24:25], off nt
	global_load_dword v89, v[82:83], off offset:2048 nt
	s_nop 0
	global_load_dword v14, v[84:85], off nt
	global_load_dword v15, v[96:97], off offset:2048 nt
	v_add_co_u32_e32 v8, vcc, s62, v6
	s_nop 1
	v_addc_co_u32_e32 v9, vcc, 0, v7, vcc
	v_add_co_u32_e32 v10, vcc, s85, v6
	s_nop 1
	v_addc_co_u32_e32 v11, vcc, 0, v7, vcc
	v_add_co_u32_e32 v12, vcc, s86, v6
	s_nop 1
	v_addc_co_u32_e32 v13, vcc, 0, v7, vcc
	v_add_co_u32_e32 v24, vcc, s87, v6
	s_nop 1
	v_addc_co_u32_e32 v25, vcc, 0, v7, vcc
	v_add_co_u32_e32 v82, vcc, s88, v6
	s_nop 1
	v_addc_co_u32_e32 v83, vcc, 0, v7, vcc
	v_add_co_u32_e32 v96, vcc, s89, v6
	s_nop 1
	v_addc_co_u32_e32 v97, vcc, 0, v7, vcc
	v_add_co_u32_e32 v98, vcc, s90, v6
	s_nop 1
	v_addc_co_u32_e32 v99, vcc, 0, v7, vcc
	v_add_co_u32_e32 v100, vcc, s91, v6
	s_nop 1
	v_addc_co_u32_e32 v101, vcc, 0, v7, vcc
	global_load_dword v85, v[8:9], off nt
	global_load_dword v87, v[10:11], off offset:2048 nt
	s_nop 0
	global_load_dword v12, v[12:13], off nt
	s_nop 0
	global_load_dword v13, v[24:25], off offset:2048 nt
	s_nop 0
	global_load_dword v83, v[82:83], off nt
	s_nop 0
	global_load_dword v84, v[96:97], off offset:2048 nt
	global_load_dword v10, v[98:99], off nt
	global_load_dword v11, v[100:101], off offset:2048 nt
	v_add_co_u32_e32 v8, vcc, s92, v6
	s_nop 1
	v_addc_co_u32_e32 v9, vcc, 0, v7, vcc
	v_add_co_u32_e32 v96, vcc, s93, v6
	s_nop 1
	v_addc_co_u32_e32 v97, vcc, 0, v7, vcc
	v_add_co_u32_e32 v98, vcc, s94, v6
	s_nop 1
	v_addc_co_u32_e32 v99, vcc, 0, v7, vcc
	v_add_co_u32_e32 v100, vcc, s95, v6
	s_nop 1
	v_addc_co_u32_e32 v101, vcc, 0, v7, vcc
	v_add_co_u32_e32 v102, vcc, s96, v6
	s_nop 1
	v_addc_co_u32_e32 v103, vcc, 0, v7, vcc
	v_add_co_u32_e32 v104, vcc, s97, v6
	s_nop 1
	v_addc_co_u32_e32 v105, vcc, 0, v7, vcc
	v_add_co_u32_e32 v106, vcc, 0x69000, v6
	s_nop 1
	v_addc_co_u32_e32 v107, vcc, 0, v7, vcc
	v_add_co_u32_e32 v108, vcc, 0x6c000, v6
	s_nop 1
	v_addc_co_u32_e32 v109, vcc, 0, v7, vcc
	global_load_dword v25, v[8:9], off nt
	global_load_dword v82, v[96:97], off offset:2048 nt
	s_nop 0
	global_load_dword v8, v[98:99], off nt
	global_load_dword v9, v[100:101], off offset:2048 nt
	global_load_dword v4, v[102:103], off nt
	global_load_dword v24, v[104:105], off offset:2048 nt
	global_load_dword v6, v[106:107], off nt
	global_load_dword v7, v[108:109], off offset:2048 nt
	s_load_dwordx2 s[20:21], s[4:5], 0x10
	v_readfirstlane_b32 s4, v110
	v_readfirstlane_b32 s5, v111
	v_add_u32_e32 v96, v26, v34
	s_waitcnt lgkmcnt(0)
	s_cmp_lg_u64 s[20:21], 0
	s_cselect_b64 s[22:23], -1, 0
	s_cmp_eq_u64 s[20:21], 0
	s_cbranch_scc1 .LBB0_125
	v_lshlrev_b32_e32 v97, 2, v22
	global_load_dword v98, v81, s[20:21] offset:8 nt
	global_load_dword v22, v81, s[20:21] offset:16 nt
	global_load_dword v23, v81, s[20:21] offset:24 nt
	s_nop 0
	global_load_dword v97, v97, s[20:21] nt
	s_waitcnt vmcnt(3)
	v_mul_f32_e32 v98, v95, v98
	s_waitcnt vmcnt(1)
	v_pk_mul_f32 v[22:23], v[20:21], v[22:23]
	s_waitcnt vmcnt(0)
	v_mul_f32_e32 v97, v94, v97
	ds_write_b32 v27, v97
	ds_write_b32 v96, v98
	s_load_dwordx2 s[18:19], s[4:5], 0xc0
	s_cbranch_execnz .LBB0_100

.LBB0_100:
	s_waitcnt vmcnt(29)
	v_add_u32_e32 v20, v26, v36
	ds_write2_b32 v20, v22, v23 offset1:66
	v_cndmask_b32_e64 v20, 0, 1, s[22:23]
	v_cmp_ne_u32_e64 s[4:5], 1, v20
	s_andn2_b64 vcc, exec, s[22:23]
	v_add_u32_e32 v22, v26, v39
	s_cbranch_vccnz .LBB0_126
	global_load_dword v23, v81, s[20:21] offset:32 nt
	global_load_dword v94, v81, s[20:21] offset:40 nt
	global_load_dword v20, v81, s[20:21] offset:48 nt
	global_load_dword v21, v81, s[20:21] offset:56 nt
	s_waitcnt vmcnt(3)
	v_mul_f32_e32 v23, v92, v23
	s_waitcnt vmcnt(2)
	v_mul_f32_e32 v94, v93, v94
	ds_write2_b32 v22, v23, v94 offset1:66
	s_waitcnt vmcnt(0)
	v_pk_mul_f32 v[20:21], v[18:19], v[20:21]
	s_cbranch_execnz .LBB0_103

.LBB0_103:
	s_waitcnt vmcnt(25)
	v_add_u32_e32 v18, v26, v42
	ds_write2_b32 v18, v20, v21 offset1:66
	s_and_b64 vcc, exec, s[4:5]
	v_add_u32_e32 v20, v26, v45
	s_cbranch_vccnz .LBB0_127
	global_load_dword v21, v81, s[20:21] offset:64 nt
	global_load_dword v22, v81, s[20:21] offset:72 nt
	global_load_dword v18, v81, s[20:21] offset:80 nt
	global_load_dword v19, v81, s[20:21] offset:88 nt
	s_waitcnt vmcnt(3)
	v_mul_f32_e32 v21, v90, v21
	s_waitcnt vmcnt(2)
	v_mul_f32_e32 v22, v91, v22
	ds_write2_b32 v20, v21, v22 offset1:66
	s_waitcnt vmcnt(0)
	v_pk_mul_f32 v[18:19], v[16:17], v[18:19]
	s_cbranch_execnz .LBB0_106

.LBB0_106:
	s_waitcnt vmcnt(21)
	v_add_u32_e32 v16, v26, v48
	ds_write2_b32 v16, v18, v19 offset1:66
	s_and_b64 vcc, exec, s[4:5]
	v_add_u32_e32 v18, v26, v51
	s_cbranch_vccnz .LBB0_128
	global_load_dword v19, v81, s[20:21] offset:96 nt
	global_load_dword v20, v81, s[20:21] offset:104 nt
	global_load_dword v16, v81, s[20:21] offset:112 nt
	global_load_dword v17, v81, s[20:21] offset:120 nt
	s_waitcnt vmcnt(3)
	v_mul_f32_e32 v19, v88, v19
	s_waitcnt vmcnt(2)
	v_mul_f32_e32 v20, v89, v20
	ds_write2_b32 v18, v19, v20 offset1:66
	s_waitcnt vmcnt(0)
	v_pk_mul_f32 v[16:17], v[14:15], v[16:17]
	s_cbranch_execnz .LBB0_109

.LBB0_109:
	s_waitcnt vmcnt(17)
	v_add_u32_e32 v14, v26, v54
	ds_write2_b32 v14, v16, v17 offset1:66
	s_and_b64 vcc, exec, s[4:5]
	v_add_u32_e32 v16, v26, v57
	s_cbranch_vccnz .LBB0_129
	global_load_dword v17, v81, s[20:21] offset:128 nt
	global_load_dword v18, v81, s[20:21] offset:136 nt
	global_load_dword v14, v81, s[20:21] offset:144 nt
	global_load_dword v15, v81, s[20:21] offset:152 nt
	s_waitcnt vmcnt(3)
	v_mul_f32_e32 v17, v85, v17
	s_waitcnt vmcnt(2)
	v_mul_f32_e32 v18, v87, v18
	ds_write2_b32 v16, v17, v18 offset1:66
	s_waitcnt vmcnt(0)
	v_pk_mul_f32 v[14:15], v[12:13], v[14:15]
	s_cbranch_execnz .LBB0_112

.LBB0_112:
	s_waitcnt vmcnt(13)
	v_add_u32_e32 v12, v26, v60
	ds_write2_b32 v12, v14, v15 offset1:66
	s_and_b64 vcc, exec, s[4:5]
	v_add_u32_e32 v14, v26, v63
	s_cbranch_vccnz .LBB0_130
	global_load_dword v15, v81, s[20:21] offset:160 nt
	global_load_dword v16, v81, s[20:21] offset:168 nt
	global_load_dword v12, v81, s[20:21] offset:176 nt
	global_load_dword v13, v81, s[20:21] offset:184 nt
	s_waitcnt vmcnt(3)
	v_mul_f32_e32 v15, v83, v15
	s_waitcnt vmcnt(2)
	v_mul_f32_e32 v16, v84, v16
	ds_write2_b32 v14, v15, v16 offset1:66
	s_waitcnt vmcnt(0)
	v_pk_mul_f32 v[12:13], v[10:11], v[12:13]
	s_cbranch_execnz .LBB0_115

.LBB0_115:
	s_waitcnt vmcnt(9)
	v_add_u32_e32 v10, v26, v66
	ds_write2_b32 v10, v12, v13 offset1:66
	s_and_b64 vcc, exec, s[4:5]
	v_add_u32_e32 v12, v26, v69
	s_cbranch_vccnz .LBB0_131
	global_load_dword v13, v81, s[20:21] offset:192 nt
	global_load_dword v14, v81, s[20:21] offset:200 nt
	global_load_dword v10, v81, s[20:21] offset:208 nt
	global_load_dword v11, v81, s[20:21] offset:216 nt
	s_waitcnt vmcnt(3)
	v_mul_f32_e32 v13, v25, v13
	s_waitcnt vmcnt(2)
	v_mul_f32_e32 v14, v82, v14
	ds_write2_b32 v12, v13, v14 offset1:66
	s_waitcnt vmcnt(0)
	v_pk_mul_f32 v[10:11], v[8:9], v[10:11]
	s_cbranch_execnz .LBB0_118

.LBB0_118:
	s_waitcnt vmcnt(8)
	ds_write2_b32 v12, v10, v11 offset0:132 offset1:198
	s_and_b64 vcc, exec, s[4:5]
	v_add_u32_e32 v10, 0x400, v12
	s_cbranch_vccnz .LBB0_132
	global_load_dword v11, v81, s[20:21] offset:224 nt
	global_load_dword v12, v81, s[20:21] offset:232 nt
	global_load_dword v8, v81, s[20:21] offset:240 nt
	global_load_dword v9, v81, s[20:21] offset:248 nt
	s_waitcnt vmcnt(3)
	v_mul_f32_e32 v11, v4, v11
	s_waitcnt vmcnt(2)
	v_mul_f32_e32 v12, v24, v12
	ds_write2_b32 v10, v11, v12 offset0:8 offset1:74
	s_waitcnt vmcnt(0)
	v_pk_mul_f32 v[8:9], v[6:7], v[8:9]
	s_cbranch_execnz .LBB0_121

.LBB0_123:
	s_andn2_b64 vcc, exec, s[4:5]
	s_cbranch_vccnz .LBB0_20
	s_ashr_i32 s4, s38, 31
	s_lshr_b32 s4, s4, 24
	s_add_i32 s4, s38, s4
	s_ashr_i32 s18, s4, 8
	s_and_b32 s4, s4, 0xff00
	s_sub_i32 s8, s38, s4
	s_sext_i32_i16 s4, s8
	s_bfe_u32 s4, s4, 0x4001b
	s_add_i32 s4, s8, s4
	v_mov_b32_e32 v4, s0
	v_mov_b32_e32 v6, s1
	s_sext_i32_i16 s22, s4
	s_and_b32 s19, s4, 0xfff0
	s_sub_i32 s8, s8, s19
	v_readfirstlane_b32 s4, v4
	v_readfirstlane_b32 s5, v6
	s_load_dwordx2 s[4:5], s[4:5], 0x38
	s_ashr_i32 s19, s18, 31
	s_lshl_b64 s[20:21], s[18:19], 21
	s_sext_i32_i16 s8, s8
	v_lshlrev_b32_e32 v4, 2, v0
	s_waitcnt lgkmcnt(0)
	s_add_u32 s23, s4, s20
	s_addc_u32 s5, s5, s21
	s_lshl_b32 s4, s22, 2
	s_lshl_b32 s20, s8, 5
	s_andn2_b32 s4, s4, 63
	s_lshl_b32 s8, s18, 9
	s_ashr_i32 s21, s20, 31
	s_add_i32 s8, s20, s8
	v_or_b32_e32 v6, s4, v3
	s_lshl_b64 s[18:19], s[20:21], 2
	s_add_u32 s18, s23, s18
	v_or_b32_e32 v12, 2, v6
	v_or_b32_e32 v14, 4, v6
	v_or_b32_e32 v16, 6, v6
	v_or_b32_e32 v18, 8, v6
	v_or_b32_e32 v20, 10, v6
	v_or_b32_e32 v22, 12, v6
	v_or_b32_e32 v24, 14, v6
	s_addc_u32 s19, s5, s19
	v_ashrrev_i32_e32 v7, 31, v6
	v_ashrrev_i32_e32 v13, 31, v12
	v_ashrrev_i32_e32 v15, 31, v14
	v_ashrrev_i32_e32 v17, 31, v16
	v_ashrrev_i32_e32 v19, 31, v18
	v_ashrrev_i32_e32 v21, 31, v20
	v_ashrrev_i32_e32 v23, 31, v22
	v_ashrrev_i32_e32 v25, 31, v24
	v_lshl_add_u64 v[8:9], s[18:19], 0, v[4:5]
	v_lshlrev_b64 v[10:11], 11, v[6:7]
	v_lshlrev_b64 v[12:13], 11, v[12:13]
	v_lshlrev_b64 v[14:15], 11, v[14:15]
	v_lshlrev_b64 v[16:17], 11, v[16:17]
	v_lshlrev_b64 v[18:19], 11, v[18:19]
	v_lshlrev_b64 v[20:21], 11, v[20:21]
	v_lshlrev_b64 v[22:23], 11, v[22:23]
	v_lshlrev_b64 v[24:25], 11, v[24:25]
	v_mov_b32_e32 v81, s0
	v_mov_b32_e32 v82, s1
	v_lshl_add_u64 v[10:11], v[8:9], 0, v[10:11]
	v_lshl_add_u64 v[12:13], v[8:9], 0, v[12:13]
	v_lshl_add_u64 v[14:15], v[8:9], 0, v[14:15]
	v_lshl_add_u64 v[16:17], v[8:9], 0, v[16:17]
	v_lshl_add_u64 v[18:19], v[8:9], 0, v[18:19]
	v_lshl_add_u64 v[20:21], v[8:9], 0, v[20:21]
	v_lshl_add_u64 v[22:23], v[8:9], 0, v[22:23]
	v_lshl_add_u64 v[24:25], v[8:9], 0, v[24:25]
	global_load_dword v4, v[10:11], off nt
	global_load_dword v83, v[12:13], off nt
	global_load_dword v84, v[14:15], off nt
	global_load_dword v85, v[16:17], off nt
	global_load_dword v87, v[18:19], off nt
	global_load_dword v88, v[20:21], off nt
	global_load_dword v89, v[22:23], off nt
	global_load_dword v90, v[24:25], off nt
	v_or_b32_e32 v10, 16, v6
	v_or_b32_e32 v12, 18, v6
	v_or_b32_e32 v14, 20, v6
	v_or_b32_e32 v16, 22, v6
	v_or_b32_e32 v18, 24, v6
	v_or_b32_e32 v20, 26, v6
	v_or_b32_e32 v22, 28, v6
	v_or_b32_e32 v24, 30, v6
	v_ashrrev_i32_e32 v11, 31, v10
	v_ashrrev_i32_e32 v13, 31, v12
	v_ashrrev_i32_e32 v15, 31, v14
	v_ashrrev_i32_e32 v17, 31, v16
	v_ashrrev_i32_e32 v19, 31, v18
	v_ashrrev_i32_e32 v21, 31, v20
	v_ashrrev_i32_e32 v23, 31, v22
	v_ashrrev_i32_e32 v25, 31, v24
	v_lshlrev_b64 v[10:11], 11, v[10:11]
	v_lshlrev_b64 v[12:13], 11, v[12:13]
	v_lshlrev_b64 v[14:15], 11, v[14:15]
	v_lshlrev_b64 v[16:17], 11, v[16:17]
	v_lshlrev_b64 v[18:19], 11, v[18:19]
	v_lshlrev_b64 v[20:21], 11, v[20:21]
	v_lshlrev_b64 v[22:23], 11, v[22:23]
	v_lshlrev_b64 v[24:25], 11, v[24:25]
	v_lshl_add_u64 v[10:11], v[8:9], 0, v[10:11]
	v_lshl_add_u64 v[12:13], v[8:9], 0, v[12:13]
	v_lshl_add_u64 v[14:15], v[8:9], 0, v[14:15]
	v_lshl_add_u64 v[16:17], v[8:9], 0, v[16:17]
	v_lshl_add_u64 v[18:19], v[8:9], 0, v[18:19]
	v_lshl_add_u64 v[20:21], v[8:9], 0, v[20:21]
	v_lshl_add_u64 v[22:23], v[8:9], 0, v[22:23]
	v_lshl_add_u64 v[24:25], v[8:9], 0, v[24:25]
	global_load_dword v91, v[10:11], off nt
	global_load_dword v92, v[12:13], off nt
	global_load_dword v93, v[14:15], off nt
	global_load_dword v94, v[16:17], off nt
	global_load_dword v95, v[18:19], off nt
	global_load_dword v96, v[20:21], off nt
	global_load_dword v97, v[22:23], off nt
	global_load_dword v98, v[24:25], off nt
	v_or_b32_e32 v10, 32, v6
	v_or_b32_e32 v12, 34, v6
	v_or_b32_e32 v14, 36, v6
	v_or_b32_e32 v16, 38, v6
	v_or_b32_e32 v18, 40, v6
	v_or_b32_e32 v20, 42, v6
	v_or_b32_e32 v22, 44, v6
	v_or_b32_e32 v24, 46, v6
	v_ashrrev_i32_e32 v11, 31, v10
	v_ashrrev_i32_e32 v13, 31, v12
	v_ashrrev_i32_e32 v15, 31, v14
	v_ashrrev_i32_e32 v17, 31, v16
	v_ashrrev_i32_e32 v19, 31, v18
	v_ashrrev_i32_e32 v21, 31, v20
	v_ashrrev_i32_e32 v23, 31, v22
	v_ashrrev_i32_e32 v25, 31, v24
	v_lshlrev_b64 v[10:11], 11, v[10:11]
	v_lshlrev_b64 v[12:13], 11, v[12:13]
	v_lshlrev_b64 v[14:15], 11, v[14:15]
	v_lshlrev_b64 v[16:17], 11, v[16:17]
	v_lshlrev_b64 v[18:19], 11, v[18:19]
	v_lshlrev_b64 v[20:21], 11, v[20:21]
	v_lshlrev_b64 v[22:23], 11, v[22:23]
	v_lshlrev_b64 v[24:25], 11, v[24:25]
	v_lshl_add_u64 v[10:11], v[8:9], 0, v[10:11]
	v_lshl_add_u64 v[12:13], v[8:9], 0, v[12:13]
	v_lshl_add_u64 v[14:15], v[8:9], 0, v[14:15]
	v_lshl_add_u64 v[16:17], v[8:9], 0, v[16:17]
	v_lshl_add_u64 v[18:19], v[8:9], 0, v[18:19]
	v_lshl_add_u64 v[20:21], v[8:9], 0, v[20:21]
	v_lshl_add_u64 v[22:23], v[8:9], 0, v[22:23]
	v_lshl_add_u64 v[24:25], v[8:9], 0, v[24:25]
	global_load_dword v99, v[10:11], off nt
	global_load_dword v100, v[12:13], off nt
	global_load_dword v101, v[14:15], off nt
	global_load_dword v102, v[16:17], off nt
	global_load_dword v103, v[18:19], off nt
	global_load_dword v104, v[20:21], off nt
	global_load_dword v105, v[22:23], off nt
	s_nop 0
	global_load_dword v24, v[24:25], off nt
	v_or_b32_e32 v10, 48, v6
	v_or_b32_e32 v12, 50, v6
	v_or_b32_e32 v14, 52, v6
	v_or_b32_e32 v16, 54, v6
	v_or_b32_e32 v18, 56, v6
	v_or_b32_e32 v20, 58, v6
	v_or_b32_e32 v22, 60, v6
	v_or_b32_e32 v6, 62, v6
	v_ashrrev_i32_e32 v11, 31, v10
	v_ashrrev_i32_e32 v13, 31, v12
	v_ashrrev_i32_e32 v15, 31, v14
	v_ashrrev_i32_e32 v7, 31, v6
	v_lshlrev_b64 v[10:11], 11, v[10:11]
	v_lshlrev_b64 v[12:13], 11, v[12:13]
	v_lshlrev_b64 v[14:15], 11, v[14:15]
	v_ashrrev_i32_e32 v17, 31, v16
	v_ashrrev_i32_e32 v19, 31, v18
	v_ashrrev_i32_e32 v21, 31, v20
	v_ashrrev_i32_e32 v23, 31, v22
	v_lshlrev_b64 v[6:7], 11, v[6:7]
	v_lshl_add_u64 v[10:11], v[8:9], 0, v[10:11]
	v_lshl_add_u64 v[12:13], v[8:9], 0, v[12:13]
	v_lshl_add_u64 v[14:15], v[8:9], 0, v[14:15]
	v_lshlrev_b64 v[16:17], 11, v[16:17]
	v_lshlrev_b64 v[18:19], 11, v[18:19]
	v_lshlrev_b64 v[20:21], 11, v[20:21]
	v_lshlrev_b64 v[22:23], 11, v[22:23]
	v_lshl_add_u64 v[6:7], v[8:9], 0, v[6:7]
	v_lshl_add_u64 v[16:17], v[8:9], 0, v[16:17]
	v_lshl_add_u64 v[18:19], v[8:9], 0, v[18:19]
	v_lshl_add_u64 v[20:21], v[8:9], 0, v[20:21]
	v_lshl_add_u64 v[22:23], v[8:9], 0, v[22:23]
	global_load_dword v8, v[10:11], off nt
	global_load_dword v9, v[12:13], off nt
	s_nop 0
	global_load_dword v10, v[14:15], off nt
	global_load_dword v11, v[16:17], off nt
	global_load_dword v12, v[18:19], off nt
	global_load_dword v13, v[20:21], off nt
	s_nop 0
	global_load_dword v14, v[22:23], off nt
	s_nop 0
	global_load_dword v6, v[6:7], off nt
	v_readfirstlane_b32 s18, v81
	v_readfirstlane_b32 s19, v82
	s_load_dwordx2 s[18:19], s[18:19], 0xc0
	s_waitcnt vmcnt(30)
	ds_write2_b32 v27, v4, v83 offset1:66
	s_waitcnt vmcnt(28)
	ds_write2_b32 v27, v84, v85 offset0:132 offset1:198
	v_add_u32_e32 v4, 0x400, v27
	s_waitcnt vmcnt(26)
	ds_write2_b32 v4, v87, v88 offset0:8 offset1:74
	s_waitcnt vmcnt(24)
	ds_write2_b32 v4, v89, v90 offset0:140 offset1:206
	v_add_u32_e32 v4, 0x800, v27
	s_waitcnt vmcnt(22)
	ds_write2_b32 v4, v91, v92 offset0:16 offset1:82
	s_waitcnt vmcnt(20)
	ds_write2_b32 v4, v93, v94 offset0:148 offset1:214
	v_add_u32_e32 v4, 0xc00, v27
	s_waitcnt vmcnt(18)
	ds_write2_b32 v4, v95, v96 offset0:24 offset1:90
	s_waitcnt vmcnt(16)
	ds_write2_b32 v4, v97, v98 offset0:156 offset1:222
	v_add_u32_e32 v4, 0x1000, v27
	s_waitcnt vmcnt(14)
	ds_write2_b32 v4, v99, v100 offset0:32 offset1:98
	s_waitcnt vmcnt(12)
	ds_write2_b32 v4, v101, v102 offset0:164 offset1:230
	v_add_u32_e32 v4, 0x1400, v27
	s_waitcnt vmcnt(10)
	ds_write2_b32 v4, v103, v104 offset0:40 offset1:106
	s_waitcnt vmcnt(8)
	ds_write2_b32 v4, v105, v24 offset0:172 offset1:238
	v_add_u32_e32 v4, 0x1800, v27
	s_waitcnt vmcnt(6)
	ds_write2_b32 v4, v8, v9 offset0:48 offset1:114
	s_waitcnt vmcnt(4)
	ds_write2_b32 v4, v10, v11 offset0:180 offset1:246
	v_add_u32_e32 v4, 0x1c00, v27
	s_waitcnt vmcnt(2)
	ds_write2_b32 v4, v12, v13 offset0:56 offset1:122
	s_waitcnt vmcnt(0)
	ds_write2_b32 v4, v14, v6 offset0:188 offset1:254
	s_waitcnt lgkmcnt(0)
	ds_read2_b32 v[6:7], v29 offset1:33
	s_waitcnt lgkmcnt(0)
	v_cvt_pk_bf16_f32 v6, v6, v7
	ds_read2_b32 v[8:9], v29 offset0:66 offset1:99
	s_ashr_i32 s5, s4, 31
	s_waitcnt lgkmcnt(0)
	v_cvt_pk_bf16_f32 v7, v8, v9
	ds_read2_b32 v[8:9], v29 offset0:132 offset1:165
	s_lshl_b64 s[4:5], s[4:5], 1
	s_add_u32 s4, s18, s4
	s_waitcnt lgkmcnt(0)
	v_cvt_pk_bf16_f32 v8, v8, v9
	ds_read2_b32 v[10:11], v29 offset0:198 offset1:231
	s_addc_u32 s5, s19, s5
	v_lshlrev_b32_e32 v4, 1, v2
	s_waitcnt lgkmcnt(0)
	v_cvt_pk_bf16_f32 v9, v10, v11
	v_or_b32_e32 v10, s8, v28
	v_lshl_add_u64 v[12:13], s[4:5], 0, v[4:5]
	v_ashrrev_i32_e32 v11, 31, v10
	v_lshl_add_u64 v[12:13], v[12:13], 0, s[16:17]
	v_lshlrev_b64 v[10:11], 11, v[10:11]
	v_lshl_add_u64 v[10:11], v[12:13], 0, v[10:11]
	ds_read2_b32 v[14:15], v29 offset0:8 offset1:41
	global_store_dwordx4 v[10:11], v[6:9], off
	s_waitcnt lgkmcnt(0)
	s_nop 0
	v_cvt_pk_bf16_f32 v6, v14, v15
	ds_read2_b32 v[8:9], v29 offset0:74 offset1:107
	s_waitcnt lgkmcnt(0)
	v_cvt_pk_bf16_f32 v7, v8, v9
	ds_read2_b32 v[8:9], v29 offset0:140 offset1:173
	s_waitcnt lgkmcnt(0)
	v_cvt_pk_bf16_f32 v8, v8, v9
	ds_read2_b32 v[10:11], v29 offset0:206 offset1:239
	s_waitcnt lgkmcnt(0)
	v_cvt_pk_bf16_f32 v9, v10, v11
	v_or_b32_e32 v10, s8, v30
	v_ashrrev_i32_e32 v11, 31, v10
	v_lshlrev_b64 v[10:11], 11, v[10:11]
	v_lshl_add_u64 v[10:11], v[12:13], 0, v[10:11]
	ds_read2_b32 v[14:15], v29 offset0:16 offset1:49
	global_store_dwordx4 v[10:11], v[6:9], off
	s_waitcnt lgkmcnt(0)
	s_nop 0
	v_cvt_pk_bf16_f32 v6, v14, v15
	ds_read2_b32 v[8:9], v29 offset0:82 offset1:115
	s_waitcnt lgkmcnt(0)
	v_cvt_pk_bf16_f32 v7, v8, v9
	ds_read2_b32 v[8:9], v29 offset0:148 offset1:181
	s_waitcnt lgkmcnt(0)
	v_cvt_pk_bf16_f32 v8, v8, v9
	ds_read2_b32 v[10:11], v29 offset0:214 offset1:247
	s_waitcnt lgkmcnt(0)
	v_cvt_pk_bf16_f32 v9, v10, v11
	v_or_b32_e32 v10, s8, v31
	v_ashrrev_i32_e32 v11, 31, v10
	v_lshlrev_b64 v[10:11], 11, v[10:11]
	v_lshl_add_u64 v[10:11], v[12:13], 0, v[10:11]
	ds_read2_b32 v[14:15], v29 offset0:24 offset1:57
	global_store_dwordx4 v[10:11], v[6:9], off
	s_waitcnt lgkmcnt(0)
	s_nop 0
	v_cvt_pk_bf16_f32 v6, v14, v15
	ds_read2_b32 v[8:9], v29 offset0:90 offset1:123
	s_waitcnt lgkmcnt(0)
	v_cvt_pk_bf16_f32 v7, v8, v9
	ds_read2_b32 v[8:9], v29 offset0:156 offset1:189
	s_waitcnt lgkmcnt(0)
	v_cvt_pk_bf16_f32 v8, v8, v9
	ds_read2_b32 v[10:11], v29 offset0:222 offset1:255
	s_waitcnt lgkmcnt(0)
	v_cvt_pk_bf16_f32 v9, v10, v11
	v_or_b32_e32 v10, s8, v32
	v_ashrrev_i32_e32 v11, 31, v10
	v_lshlrev_b64 v[10:11], 11, v[10:11]
	v_lshl_add_u64 v[10:11], v[12:13], 0, v[10:11]
	global_store_dwordx4 v[10:11], v[6:9], off
	s_waitcnt lgkmcnt(0)
	s_branch .LBB0_20

.LBB0_160:
	v_mov_b32_e32 v5, v1
	v_mov_b32_e32 v9, v6
	v_add_u32_e32 v0, s4, v0
	v_readfirstlane_b32 s22, v5
	v_readfirstlane_b32 s23, v9
	s_load_dwordx2 s[22:23], s[22:23], 0x78
	v_mov_b32_e32 v9, v1
	v_cmp_lt_i32_e32 vcc, s20, v0
	s_or_b64 s[12:13], vcc, s[12:13]
	s_waitcnt lgkmcnt(0)
	v_lshl_add_u64 v[10:11], s[22:23], 0, v[2:3]
	global_load_dword v5, v[10:11], off nt
	v_mov_b32_e32 v10, v6
	s_waitcnt vmcnt(0)
	v_mul_f32_e64 v12, |v5|, s5
	v_readfirstlane_b32 s22, v9
	v_readfirstlane_b32 s23, v10
	s_load_dwordx2 s[22:23], s[22:23], 0xc0
	v_fma_f32 v13, |v5|, s5, -v12
	v_rndne_f32_e32 v14, v12
	v_fma_f32 v13, |v5|, s7, v13
	v_sub_f32_e32 v12, v12, v14
	v_add_f32_e32 v12, v12, v13
	v_cvt_i32_f32_e32 v14, v14
	v_exp_f32_e32 v12, v12
	s_waitcnt lgkmcnt(0)
	v_lshl_add_u64 v[10:11], s[22:23], 0, v[2:3]
	v_add_co_u32_e32 v10, vcc, 0x2f20000, v10
	v_ldexp_f32 v12, v12, v14
	s_nop 0
	v_addc_co_u32_e32 v11, vcc, 0, v11, vcc
	v_cmp_ngt_f32_e64 vcc, |v5|, s14
	v_max_f32_e32 v9, v5, v5
	v_min_f32_e32 v9, 0, v9
	v_cndmask_b32_e32 v12, 0, v12, vcc
	v_cmp_nlt_f32_e64 vcc, |v5|, s15
	v_lshl_add_u64 v[2:3], v[2:3], 0, s[10:11]
	s_nop 0
	v_cndmask_b32_e32 v26, v7, v12, vcc
	v_add_f32_e32 v5, 1.0, v26
	v_add_f32_e32 v14, -1.0, v5
	v_frexp_mant_f32_e32 v15, v5
	v_cvt_f64_f32_e32 v[12:13], v5
	v_sub_f32_e32 v16, v14, v5
	v_frexp_exp_i32_f64_e32 v12, v[12:13]
	v_cmp_gt_f32_e32 vcc, s17, v15
	v_sub_f32_e32 v14, v26, v14
	v_add_f32_e32 v13, 1.0, v16
	v_subbrev_co_u32_e32 v12, vcc, 0, v12, vcc
	v_add_f32_e32 v13, v14, v13
	v_sub_u32_e32 v14, 0, v12
	v_ldexp_f32 v5, v5, v14
	v_ldexp_f32 v13, v13, v14
	v_add_f32_e32 v14, -1.0, v5
	v_add_f32_e32 v16, 1.0, v5
	v_add_f32_e32 v15, 1.0, v14
	v_add_f32_e32 v17, -1.0, v16
	v_sub_f32_e32 v15, v5, v15
	v_sub_f32_e32 v5, v5, v17
	v_add_f32_e32 v5, v13, v5
	v_add_f32_e32 v17, v13, v15
	v_add_f32_e32 v13, v16, v5
	v_rcp_f32_e32 v20, v13
	v_add_f32_e32 v15, v14, v17
	v_sub_f32_e32 v16, v16, v13
	v_add_f32_e32 v5, v5, v16
	v_mul_f32_e32 v22, v15, v20
	v_mul_f32_e32 v16, v13, v22
	v_fma_f32 v18, v22, v13, -v16
	v_sub_f32_e32 v14, v14, v15
	v_fmac_f32_e32 v18, v22, v5
	v_add_f32_e32 v21, v17, v14
	v_add_f32_e32 v14, v16, v18
	v_sub_f32_e32 v17, v15, v14
	v_mov_b32_e32 v19, v14
	v_pk_add_f32 v[14:15], v[14:15], v[16:17] neg_lo:[0,1] neg_hi:[0,1]
	v_cvt_f32_i32_e32 v12, v12
	v_pk_add_f32 v[14:15], v[14:15], v[18:19] neg_lo:[0,1] neg_hi:[0,1]
	v_cmp_neq_f32_e32 vcc, s16, v26
	v_add_f32_e32 v15, v21, v15
	v_add_f32_e32 v14, v14, v15
	v_add_f32_e32 v15, v17, v14
	v_mul_f32_e32 v19, v20, v15
	v_mul_f32_e32 v16, v13, v19
	v_fma_f32 v18, v19, v13, -v16
	v_sub_f32_e32 v17, v17, v15
	v_fmac_f32_e32 v18, v19, v5
	v_add_f32_e32 v21, v14, v17
	v_add_f32_e32 v23, v22, v19
	v_add_f32_e32 v14, v16, v18
	v_sub_f32_e32 v13, v23, v22
	v_sub_f32_e32 v17, v15, v14
	v_sub_f32_e32 v5, v19, v13
	v_mov_b32_e32 v19, v14
	v_pk_add_f32 v[14:15], v[14:15], v[16:17] neg_lo:[0,1] neg_hi:[0,1]
	s_nop 0
	v_pk_add_f32 v[14:15], v[14:15], v[18:19] neg_lo:[0,1] neg_hi:[0,1]
	s_nop 0
	v_add_f32_e32 v13, v21, v15
	v_add_f32_e32 v13, v14, v13
	v_add_f32_e32 v13, v17, v13
	v_mul_f32_e32 v13, v20, v13
	v_add_f32_e32 v5, v5, v13
	v_add_f32_e32 v13, v23, v5
	v_mul_f32_e32 v14, v13, v13
	v_sub_f32_e32 v16, v13, v23
	v_fmamk_f32 v17, v14, 0x3e9b6dac, v8
	v_ldexp_f32 v15, v13, 1
	v_sub_f32_e32 v16, v5, v16
	v_mul_f32_e32 v13, v13, v14
	v_fmaak_f32 v5, v14, v17, 0x3f2aaada
	v_ldexp_f32 v19, v16, 1
	v_pk_mul_f32 v[16:17], v[12:13], v[4:5]
	s_nop 0
	v_fma_f32 v14, v12, s18, -v16
	v_fmac_f32_e32 v14, 0xb102e308, v12
	v_pk_add_f32 v[12:13], v[16:17], v[14:15]
	v_mov_b32_e32 v18, v16
	v_sub_f32_e32 v5, v13, v15
	v_sub_f32_e32 v5, v17, v5
	v_add_f32_e32 v19, v19, v5
	v_pk_add_f32 v[20:21], v[12:13], v[16:17] neg_lo:[0,1] neg_hi:[0,1]
	v_pk_add_f32 v[16:17], v[12:13], v[18:19]
	v_mov_b32_e32 v15, v12
	v_mov_b32_e32 v21, v17
	v_pk_add_f32 v[24:25], v[14:15], v[20:21] neg_lo:[0,1] neg_hi:[0,1]
	v_pk_add_f32 v[14:15], v[14:15], v[20:21]
	v_mov_b32_e32 v23, v12
	v_pk_add_f32 v[20:21], v[14:15], v[12:13] op_sel:[1,0] op_sel_hi:[0,1] neg_lo:[0,1] neg_hi:[0,1]
	v_mov_b32_e32 v22, v19
	v_mov_b32_e32 v18, v17
	v_mov_b32_e32 v19, v15
	v_pk_mov_b32 v[12:13], v[12:13], v[20:21] op_sel:[1,0]
	v_pk_add_f32 v[16:17], v[16:17], v[20:21] op_sel_hi:[1,0] neg_lo:[0,1] neg_hi:[0,1]
	v_pk_add_f32 v[12:13], v[18:19], v[12:13] neg_lo:[0,1] neg_hi:[0,1]
	v_mov_b32_e32 v16, v24
	v_pk_add_f32 v[12:13], v[22:23], v[12:13] neg_lo:[0,1] neg_hi:[0,1]
	v_mov_b32_e32 v25, v15
	v_pk_add_f32 v[16:17], v[16:17], v[12:13]
	s_nop 0
	v_pk_add_f32 v[18:19], v[16:17], v[16:17] op_sel:[0,1] op_sel_hi:[1,0]
	s_nop 0
	v_pk_add_f32 v[14:15], v[14:15], v[18:19] op_sel:[1,0] op_sel_hi:[0,1]
	v_mov_b32_e32 v17, v14
	v_mov_b32_e32 v13, v18
	v_pk_add_f32 v[18:19], v[16:17], v[24:25] neg_lo:[0,1] neg_hi:[0,1]
	s_nop 0
	v_sub_f32_e32 v5, v16, v18
	v_pk_add_f32 v[12:13], v[12:13], v[18:19] neg_lo:[0,1] neg_hi:[0,1]
	v_sub_f32_e32 v5, v24, v5
	v_add_f32_e32 v5, v12, v5
	v_add_f32_e32 v5, v5, v13
	v_add_f32_e32 v5, v14, v5
	v_cndmask_b32_e32 v5, v7, v5, vcc
	v_cmp_lt_f32_e64 vcc, |v26|, s19
	s_nop 1
	v_cndmask_b32_e32 v5, v5, v26, vcc
	v_sub_f32_e32 v5, v9, v5
	v_mul_f32_e32 v5, 0x41000000, v5
	v_mul_f32_e32 v5, 0x3fb8aa3b, v5
	global_store_dword v[10:11], v5, off
	s_andn2_b64 exec, exec, s[12:13]
	s_cbranch_execnz .LBB0_160
.LBB0_161:
	s_or_b64 exec, exec, s[8:9]
	s_load_dwordx4 s[40:43], s[0:1], 0xc8
	v_mov_b32_e32 v2, s1
	v_mov_b32_e32 v3, s0
	v_readlane_b32 s34, v255, 2
	s_waitcnt lgkmcnt(0)
	v_readlane_b32 s42, v255, 4
	v_mov_b32_e32 v0, s0
	v_mov_b32_e32 v1, s1
	v_readfirstlane_b32 s8, v3
	v_readfirstlane_b32 s9, v2
	v_mov_b32_e32 v2, s1
	v_mov_b32_e32 v3, s0
	v_readlane_b32 s35, v255, 3
	v_readlane_b32 s43, v255, 5
	s_cmpk_gt_i32 s6, 0x7ff
	v_readfirstlane_b32 s4, v3
	v_readfirstlane_b32 s5, v2
	v_readfirstlane_b32 s10, v0
	v_readfirstlane_b32 s11, v1
	v_lshlrev_b32_e32 v72, 4, v86
	s_cbranch_scc1 .LBB0_202
	s_load_dwordx2 s[12:13], s[8:9], 0x8
	s_add_i32 s7, s6, s26
	s_cmpk_lt_i32 s7, 0x800
	v_mov_b32_e32 v73, 0
	s_cselect_b32 s8, s7, s6
	s_ashr_i32 s7, s6, 31
	s_waitcnt lgkmcnt(0)
	v_lshl_add_u64 v[74:75], s[12:13], 0, v[72:73]
	s_lshl_b64 s[12:13], s[6:7], 12
	s_ashr_i32 s9, s8, 31
	v_lshl_add_u64 v[16:17], v[74:75], 0, s[12:13]
	s_lshl_b64 s[12:13], s[8:9], 12
	v_lshl_add_u64 v[32:33], v[74:75], 0, s[12:13]
	global_load_dwordx4 v[0:3], v[16:17], off nt
	global_load_dwordx4 v[4:7], v[16:17], off offset:1024 nt
	global_load_dwordx4 v[8:11], v[16:17], off offset:2048 nt
	global_load_dwordx4 v[12:15], v[16:17], off offset:3072 nt
	s_nop 0
	global_load_dwordx4 v[16:19], v[32:33], off nt
	global_load_dwordx4 v[20:23], v[32:33], off offset:1024 nt
	global_load_dwordx4 v[24:27], v[32:33], off offset:2048 nt
	global_load_dwordx4 v[28:31], v[32:33], off offset:3072 nt
	s_load_dwordx2 s[12:13], s[10:11], 0xc0
	s_load_dwordx2 s[14:15], s[4:5], 0x30
	v_mov_b32_e32 v71, v73
	s_mov_b64 s[4:5], 0x2f20c00
	s_mul_i32 s24, s33, 40
	s_waitcnt lgkmcnt(0)
	v_lshl_add_u64 v[32:33], s[12:13], 0, v[70:71]
	v_lshl_add_u64 v[76:77], v[32:33], 0, s[4:5]
	v_mbcnt_lo_u32_b32 v32, -1, 0
	v_mbcnt_hi_u32_b32 v32, -1, v32
	v_and_b32_e32 v33, 64, v32
	v_add_u32_e32 v33, 64, v33
	v_xor_b32_e32 v34, 1, v32
	v_cmp_lt_i32_e32 vcc, v34, v33
	v_lshl_add_u64 v[78:79], s[14:15], 0, v[72:73]
	s_cmp_lg_u64 s[14:15], 0
	v_cndmask_b32_e32 v34, v32, v34, vcc
	v_lshlrev_b32_e32 v71, 2, v34
	v_xor_b32_e32 v34, 2, v32
	v_cmp_lt_i32_e32 vcc, v34, v33
	s_cselect_b64 s[10:11], -1, 0
	s_lshl_b32 s7, s33, 5
	v_cndmask_b32_e32 v34, v32, v34, vcc
	v_lshlrev_b32_e32 v73, 2, v34
	v_xor_b32_e32 v34, 4, v32
	v_cmp_lt_i32_e32 vcc, v34, v33
	s_mul_i32 s25, s33, 24
	v_mov_b32_e32 v91, 0x358637bd
	v_cndmask_b32_e32 v34, v32, v34, vcc
	v_lshlrev_b32_e32 v87, 2, v34
	v_xor_b32_e32 v34, 8, v32
	v_cmp_lt_i32_e32 vcc, v34, v33
	s_mov_b32 s15, s6
	s_mov_b32 s16, s6
	v_cndmask_b32_e32 v34, v32, v34, vcc
	v_lshlrev_b32_e32 v88, 2, v34
	v_xor_b32_e32 v34, 16, v32
	v_cmp_lt_i32_e32 vcc, v34, v33
	s_nop 1
	v_cndmask_b32_e32 v34, v32, v34, vcc
	v_lshlrev_b32_e32 v89, 2, v34
	v_xor_b32_e32 v34, 32, v32
	v_cmp_lt_i32_e32 vcc, v34, v33
	s_nop 1
	v_cndmask_b32_e32 v32, v32, v34, vcc
	v_lshlrev_b32_e32 v90, 2, v32
	s_branch .LBB0_165

.LBB0_165:
	s_add_i32 s18, s15, s3
	s_cmpk_lt_i32 s18, 0x800
	s_cselect_b64 s[20:21], -1, 0
	s_cmpk_gt_i32 s18, 0x7ff
	s_cbranch_scc1 .LBB0_167
	s_add_i32 s4, s25, s15
	s_cmpk_lt_i32 s4, 0x800
	s_cselect_b32 s12, s4, s18
	s_ashr_i32 s19, s18, 31
	s_lshl_b64 s[4:5], s[18:19], 12
	s_ashr_i32 s13, s12, 31
	v_lshl_add_u64 v[48:49], v[74:75], 0, s[4:5]
	s_lshl_b64 s[4:5], s[12:13], 12
	v_lshl_add_u64 v[64:65], v[74:75], 0, s[4:5]
	global_load_dwordx4 v[32:35], v[48:49], off nt
	global_load_dwordx4 v[36:39], v[48:49], off offset:1024 nt
	global_load_dwordx4 v[40:43], v[48:49], off offset:2048 nt
	global_load_dwordx4 v[44:47], v[48:49], off offset:3072 nt
	s_nop 0
	global_load_dwordx4 v[48:51], v[64:65], off nt
	global_load_dwordx4 v[52:55], v[64:65], off offset:1024 nt
	global_load_dwordx4 v[56:59], v[64:65], off offset:2048 nt
	global_load_dwordx4 v[60:63], v[64:65], off offset:3072 nt
	s_mov_b32 s14, s18
.LBB0_167:
	s_waitcnt vmcnt(7)
	v_pk_mul_f32 v[64:65], v[2:3], v[2:3]
	v_pk_mul_f32 v[66:67], v[0:1], v[0:1]
	s_andn2_b64 vcc, exec, s[10:11]
	v_pk_mov_b32 v[68:69], v[66:67], v[64:65] op_sel:[1,0]
	v_mov_b32_e32 v67, v65
	v_pk_add_f32 v[64:65], v[68:69], v[66:67]
	s_waitcnt vmcnt(6)
	v_pk_mul_f32 v[66:67], v[6:7], v[6:7]
	v_pk_add_f32 v[64:65], v[64:65], v[64:65] op_sel_hi:[0,1]
	v_pk_mul_f32 v[68:69], v[4:5], v[4:5]
	s_waitcnt vmcnt(5)
	v_mul_f32_e32 v64, v8, v8
	v_pk_mov_b32 v[80:81], v[68:69], v[66:67] op_sel:[1,0]
	v_mov_b32_e32 v69, v67
	v_pk_add_f32 v[66:67], v[80:81], v[68:69]
	v_pk_fma_f32 v[68:69], v[8:9], v[8:9], v[64:65] op_sel_hi:[1,1,0]
	v_mul_f32_e32 v64, v10, v10
	v_pk_add_f32 v[66:67], v[66:67], v[66:67] op_sel_hi:[0,1]
	v_pk_fma_f32 v[80:81], v[10:11], v[10:11], v[64:65] op_sel_hi:[1,1,0]
	s_waitcnt vmcnt(4)
	v_mul_f32_e32 v68, v12, v12
	v_mul_f32_e32 v80, v13, v13
	v_mul_f32_e32 v64, v14, v14
	v_mul_f32_e32 v66, v15, v15
	v_pk_add_f32 v[68:69], v[68:69], v[80:81]
	v_pk_add_f32 v[64:65], v[64:65], v[66:67]
	v_cndmask_b32_e64 v67, 0, 1, s[10:11]
	v_pk_add_f32 v[64:65], v[68:69], v[64:65]
	v_cmp_ne_u32_e64 s[4:5], 1, v67
	v_add_f32_e32 v64, v64, v65
	ds_bpermute_b32 v65, v71, v64
	v_mov_b32_e32 v67, 1.0
	v_mov_b32_e32 v68, 1.0
	v_mov_b32_e32 v69, 1.0
	s_waitcnt lgkmcnt(0)
	v_add_f32_e32 v64, v64, v65
	ds_bpermute_b32 v65, v73, v64
	s_waitcnt lgkmcnt(0)
	v_add_f32_e32 v64, v64, v65
	ds_bpermute_b32 v65, v87, v64
	s_waitcnt lgkmcnt(0)
	v_add_f32_e32 v64, v64, v65
	ds_bpermute_b32 v65, v88, v64
	s_waitcnt lgkmcnt(0)
	v_add_f32_e32 v65, v64, v65
	ds_bpermute_b32 v66, v89, v65
	v_mov_b32_e32 v64, 1.0
	s_waitcnt lgkmcnt(0)
	v_add_f32_e32 v65, v65, v66
	ds_bpermute_b32 v80, v90, v65
	v_mov_b32_e32 v66, 1.0
	s_cbranch_vccnz .LBB0_169
	global_load_dwordx4 v[66:69], v[78:79], off nt
.LBB0_169:
	s_waitcnt lgkmcnt(0)
	v_add_f32_e32 v65, v65, v80
	v_fmamk_f32 v65, v65, 0x3a800000, v91
	v_rsq_f32_e32 v82, v65
	s_ashr_i32 s17, s16, 31
	s_lshl_b64 s[22:23], s[16:17], 11
	v_lshl_add_u64 v[80:81], v[76:77], 0, s[22:23]
	v_pk_mul_f32 v[92:93], v[0:1], v[82:83] op_sel_hi:[1,0]
	v_pk_mul_f32 v[84:85], v[2:3], v[82:83] op_sel_hi:[1,0]
	s_waitcnt vmcnt(0)
	v_pk_mul_f32 v[66:67], v[92:93], v[66:67]
	v_pk_mul_f32 v[68:69], v[84:85], v[68:69]
	v_cvt_pk_bf16_f32 v66, v66, v67
	s_and_b64 vcc, exec, s[4:5]
	v_cvt_pk_bf16_f32 v67, v68, v69
	global_store_dwordx2 v[80:81], v[66:67], off
	v_mov_b32_e32 v65, 1.0
	v_mov_b32_e32 v66, 1.0
	v_mov_b32_e32 v67, 1.0
	s_cbranch_vccnz .LBB0_171
	global_load_dwordx4 v[64:67], v[78:79], off offset:1024 nt
.LBB0_171:
	v_mov_b32_e32 v83, v82
	v_mov_b32_e32 v84, v82
	v_mov_b32_e32 v85, v82
	v_pk_mul_f32 v[92:93], v[4:5], v[82:83]
	v_pk_mul_f32 v[68:69], v[6:7], v[84:85]
	s_waitcnt vmcnt(0)
	v_pk_mul_f32 v[64:65], v[92:93], v[64:65]
	v_pk_mul_f32 v[66:67], v[68:69], v[66:67]
	v_cvt_pk_bf16_f32 v64, v64, v65
	s_and_b64 vcc, exec, s[4:5]
	v_cvt_pk_bf16_f32 v65, v66, v67
	global_store_dwordx2 v[80:81], v[64:65], off offset:512
	v_mov_b32_e32 v64, 1.0
	v_mov_b32_e32 v66, 1.0
	v_mov_b32_e32 v67, 1.0
	v_mov_b32_e32 v68, 1.0
	v_mov_b32_e32 v69, 1.0
	s_cbranch_vccnz .LBB0_173
	global_load_dwordx4 v[66:69], v[78:79], off offset:2048 nt
.LBB0_173:
	v_pk_mul_f32 v[92:93], v[8:9], v[82:83]
	v_pk_mul_f32 v[84:85], v[10:11], v[84:85]
	s_waitcnt vmcnt(0)
	v_pk_mul_f32 v[66:67], v[92:93], v[66:67]
	v_pk_mul_f32 v[68:69], v[84:85], v[68:69]
	v_cvt_pk_bf16_f32 v66, v66, v67
	s_and_b64 vcc, exec, s[4:5]
	v_cvt_pk_bf16_f32 v67, v68, v69
	global_store_dwordx2 v[80:81], v[66:67], off offset:1024
	v_mov_b32_e32 v65, 1.0
	v_mov_b32_e32 v66, 1.0
	v_mov_b32_e32 v67, 1.0
	s_cbranch_vccnz .LBB0_175
	global_load_dwordx4 v[64:67], v[78:79], off offset:3072 nt
.LBB0_175:
	v_pk_mul_f32 v[68:69], v[18:19], v[18:19]
	v_pk_mul_f32 v[84:85], v[16:17], v[16:17]
	s_and_b64 vcc, exec, s[4:5]
	v_pk_mov_b32 v[92:93], v[84:85], v[68:69] op_sel:[1,0]
	v_mov_b32_e32 v85, v69
	v_pk_add_f32 v[68:69], v[92:93], v[84:85]
	v_pk_mul_f32 v[84:85], v[22:23], v[22:23]
	v_pk_add_f32 v[68:69], v[68:69], v[68:69] op_sel_hi:[0,1]
	v_pk_mul_f32 v[92:93], v[20:21], v[20:21]
	v_mul_f32_e32 v68, v24, v24
	v_pk_mov_b32 v[94:95], v[92:93], v[84:85] op_sel:[1,0]
	v_mov_b32_e32 v93, v85
	v_pk_add_f32 v[84:85], v[94:95], v[92:93]
	v_pk_fma_f32 v[92:93], v[24:25], v[24:25], v[68:69] op_sel_hi:[1,1,0]
	v_mul_f32_e32 v68, v26, v26
	v_pk_add_f32 v[84:85], v[84:85], v[84:85] op_sel_hi:[0,1]
	v_pk_fma_f32 v[94:95], v[26:27], v[26:27], v[68:69] op_sel_hi:[1,1,0]
	v_mul_f32_e32 v92, v28, v28
	v_mul_f32_e32 v94, v29, v29
	v_mul_f32_e32 v68, v30, v30
	v_mul_f32_e32 v84, v31, v31
	v_pk_add_f32 v[92:93], v[92:93], v[94:95]
	v_pk_add_f32 v[68:69], v[68:69], v[84:85]
	s_nop 0
	v_pk_add_f32 v[68:69], v[92:93], v[68:69]
	s_nop 0
	v_add_f32_e32 v68, v68, v69
	ds_bpermute_b32 v69, v71, v68
	s_waitcnt lgkmcnt(0)
	v_add_f32_e32 v68, v68, v69
	ds_bpermute_b32 v69, v73, v68
	s_waitcnt lgkmcnt(0)
	v_add_f32_e32 v69, v68, v69
	ds_bpermute_b32 v84, v87, v69
	v_mov_b32_e32 v68, v82
	s_waitcnt lgkmcnt(0)
	v_add_f32_e32 v84, v69, v84
	ds_bpermute_b32 v85, v88, v84
	v_mov_b32_e32 v69, v82
	v_pk_mul_f32 v[68:69], v[14:15], v[68:69]
	v_pk_mul_f32 v[82:83], v[12:13], v[82:83]
	s_waitcnt vmcnt(0)
	v_pk_mul_f32 v[66:67], v[68:69], v[66:67]
	s_waitcnt lgkmcnt(0)
	v_add_f32_e32 v68, v84, v85
	ds_bpermute_b32 v69, v89, v68
	v_pk_mul_f32 v[64:65], v[82:83], v[64:65]
	s_nop 0
	v_cvt_pk_bf16_f32 v64, v64, v65
	v_cvt_pk_bf16_f32 v65, v66, v67
	global_store_dwordx2 v[80:81], v[64:65], off offset:1536
	s_waitcnt lgkmcnt(0)
	v_add_f32_e32 v65, v68, v69
	ds_bpermute_b32 v80, v90, v65
	v_mov_b32_e32 v64, 1.0
	v_mov_b32_e32 v66, 1.0
	v_mov_b32_e32 v67, 1.0
	v_mov_b32_e32 v68, 1.0
	v_mov_b32_e32 v69, 1.0
	s_cbranch_vccnz .LBB0_177
	global_load_dwordx4 v[66:69], v[78:79], off nt
.LBB0_177:
	s_waitcnt lgkmcnt(0)
	v_add_f32_e32 v65, v65, v80
	v_fmamk_f32 v65, v65, 0x3a800000, v91
	v_rsq_f32_e32 v82, v65
	s_ashr_i32 s9, s8, 31
	s_lshl_b64 s[22:23], s[8:9], 11
	v_lshl_add_u64 v[80:81], v[76:77], 0, s[22:23]
	v_pk_mul_f32 v[92:93], v[16:17], v[82:83] op_sel_hi:[1,0]
	v_pk_mul_f32 v[84:85], v[18:19], v[82:83] op_sel_hi:[1,0]
	s_waitcnt vmcnt(0)
	v_pk_mul_f32 v[66:67], v[92:93], v[66:67]
	v_pk_mul_f32 v[68:69], v[84:85], v[68:69]
	v_cvt_pk_bf16_f32 v66, v66, v67
	s_and_b64 vcc, exec, s[4:5]
	v_cvt_pk_bf16_f32 v67, v68, v69
	global_store_dwordx2 v[80:81], v[66:67], off
	v_mov_b32_e32 v65, 1.0
	v_mov_b32_e32 v66, 1.0
	v_mov_b32_e32 v67, 1.0
	s_cbranch_vccnz .LBB0_179
	global_load_dwordx4 v[64:67], v[78:79], off offset:1024 nt
.LBB0_179:
	v_mov_b32_e32 v83, v82
	v_mov_b32_e32 v84, v82
	v_mov_b32_e32 v85, v82
	v_pk_mul_f32 v[92:93], v[20:21], v[82:83]
	v_pk_mul_f32 v[68:69], v[22:23], v[84:85]
	s_waitcnt vmcnt(0)
	v_pk_mul_f32 v[64:65], v[92:93], v[64:65]
	v_pk_mul_f32 v[66:67], v[68:69], v[66:67]
	v_cvt_pk_bf16_f32 v64, v64, v65
	s_and_b64 vcc, exec, s[4:5]
	v_cvt_pk_bf16_f32 v65, v66, v67
	global_store_dwordx2 v[80:81], v[64:65], off offset:512
	v_mov_b32_e32 v64, 1.0
	v_mov_b32_e32 v66, 1.0
	v_mov_b32_e32 v67, 1.0
	v_mov_b32_e32 v68, 1.0
	v_mov_b32_e32 v69, 1.0
	s_cbranch_vccnz .LBB0_181
	global_load_dwordx4 v[66:69], v[78:79], off offset:2048 nt
.LBB0_181:
	v_pk_mul_f32 v[92:93], v[24:25], v[82:83]
	v_pk_mul_f32 v[84:85], v[26:27], v[84:85]
	s_waitcnt vmcnt(0)
	v_pk_mul_f32 v[66:67], v[92:93], v[66:67]
	v_pk_mul_f32 v[68:69], v[84:85], v[68:69]
	v_cvt_pk_bf16_f32 v66, v66, v67
	s_and_b64 vcc, exec, s[4:5]
	v_cvt_pk_bf16_f32 v67, v68, v69
	global_store_dwordx2 v[80:81], v[66:67], off offset:1024
	v_mov_b32_e32 v65, 1.0
	v_mov_b32_e32 v66, 1.0
	v_mov_b32_e32 v67, 1.0
	s_cbranch_vccnz .LBB0_183
	global_load_dwordx4 v[64:67], v[78:79], off offset:3072 nt

.LBB0_185:
	s_add_i32 s8, s24, s15
	s_cmpk_lt_i32 s8, 0x800
	s_cselect_b32 s8, s8, s22
	s_ashr_i32 s23, s22, 31
	s_lshl_b64 s[16:17], s[22:23], 12
	s_ashr_i32 s9, s8, 31
	v_lshl_add_u64 v[16:17], v[74:75], 0, s[16:17]
	s_lshl_b64 s[16:17], s[8:9], 12
	v_lshl_add_u64 v[64:65], v[74:75], 0, s[16:17]
	global_load_dwordx4 v[0:3], v[16:17], off nt
	global_load_dwordx4 v[4:7], v[16:17], off offset:1024 nt
	global_load_dwordx4 v[8:11], v[16:17], off offset:2048 nt
	global_load_dwordx4 v[12:15], v[16:17], off offset:3072 nt
	s_nop 0
	global_load_dwordx4 v[16:19], v[64:65], off nt
	global_load_dwordx4 v[20:23], v[64:65], off offset:1024 nt
	global_load_dwordx4 v[24:27], v[64:65], off offset:2048 nt
	global_load_dwordx4 v[28:31], v[64:65], off offset:3072 nt
	s_mov_b32 s16, s22
	s_andn2_b64 vcc, exec, s[20:21]
	s_cbranch_vccnz .LBB0_164
.LBB0_186:
	v_pk_mul_f32 v[64:65], v[34:35], v[34:35]
	v_pk_mul_f32 v[66:67], v[32:33], v[32:33]
	s_and_b64 vcc, exec, s[4:5]
	v_pk_mov_b32 v[68:69], v[66:67], v[64:65] op_sel:[1,0]
	v_mov_b32_e32 v67, v65
	v_pk_add_f32 v[64:65], v[68:69], v[66:67]
	v_pk_mul_f32 v[66:67], v[38:39], v[38:39]
	v_pk_add_f32 v[64:65], v[64:65], v[64:65] op_sel_hi:[0,1]
	v_pk_mul_f32 v[68:69], v[36:37], v[36:37]
	v_mul_f32_e32 v64, v40, v40
	v_pk_mov_b32 v[80:81], v[68:69], v[66:67] op_sel:[1,0]
	v_mov_b32_e32 v69, v67
	v_pk_add_f32 v[66:67], v[80:81], v[68:69]
	v_pk_fma_f32 v[68:69], v[40:41], v[40:41], v[64:65] op_sel_hi:[1,1,0]
	v_mul_f32_e32 v64, v42, v42
	v_pk_add_f32 v[66:67], v[66:67], v[66:67] op_sel_hi:[0,1]
	v_pk_fma_f32 v[80:81], v[42:43], v[42:43], v[64:65] op_sel_hi:[1,1,0]
	v_mul_f32_e32 v68, v44, v44
	v_mul_f32_e32 v80, v45, v45
	v_mul_f32_e32 v66, v46, v46
	v_mul_f32_e32 v64, v47, v47
	v_pk_add_f32 v[68:69], v[68:69], v[80:81]
	v_pk_add_f32 v[64:65], v[66:67], v[64:65]
	v_mov_b32_e32 v67, 1.0
	v_pk_add_f32 v[64:65], v[68:69], v[64:65]
	v_mov_b32_e32 v68, 1.0
	v_add_f32_e32 v64, v64, v65
	ds_bpermute_b32 v65, v71, v64
	v_mov_b32_e32 v69, 1.0
	s_waitcnt lgkmcnt(0)
	v_add_f32_e32 v64, v64, v65
	ds_bpermute_b32 v65, v73, v64
	s_waitcnt lgkmcnt(0)
	v_add_f32_e32 v64, v64, v65
	ds_bpermute_b32 v65, v87, v64
	s_waitcnt lgkmcnt(0)
	v_add_f32_e32 v64, v64, v65
	ds_bpermute_b32 v65, v88, v64
	s_waitcnt lgkmcnt(0)
	v_add_f32_e32 v65, v64, v65
	ds_bpermute_b32 v66, v89, v65
	v_mov_b32_e32 v64, 1.0
	s_waitcnt lgkmcnt(0)
	v_add_f32_e32 v65, v65, v66
	ds_bpermute_b32 v80, v90, v65
	v_mov_b32_e32 v66, 1.0
	s_cbranch_vccnz .LBB0_188
	global_load_dwordx4 v[66:69], v[78:79], off nt
.LBB0_188:
	s_waitcnt lgkmcnt(0)
	v_add_f32_e32 v65, v65, v80
	v_fmamk_f32 v65, v65, 0x3a800000, v91
	v_rsq_f32_e32 v82, v65
	s_ashr_i32 s15, s14, 31
	s_lshl_b64 s[20:21], s[14:15], 11
	v_lshl_add_u64 v[80:81], v[76:77], 0, s[20:21]
	v_pk_mul_f32 v[92:93], v[32:33], v[82:83] op_sel_hi:[1,0]
	v_pk_mul_f32 v[84:85], v[34:35], v[82:83] op_sel_hi:[1,0]
	s_waitcnt vmcnt(0)
	v_pk_mul_f32 v[66:67], v[92:93], v[66:67]
	v_pk_mul_f32 v[68:69], v[84:85], v[68:69]
	v_cvt_pk_bf16_f32 v66, v66, v67
	s_and_b64 vcc, exec, s[4:5]
	v_cvt_pk_bf16_f32 v67, v68, v69
	global_store_dwordx2 v[80:81], v[66:67], off
	v_mov_b32_e32 v65, 1.0
	v_mov_b32_e32 v66, 1.0
	v_mov_b32_e32 v67, 1.0
	s_cbranch_vccnz .LBB0_190
	global_load_dwordx4 v[64:67], v[78:79], off offset:1024 nt
.LBB0_190:
	v_mov_b32_e32 v83, v82
	v_mov_b32_e32 v84, v82
	v_mov_b32_e32 v85, v82
	v_pk_mul_f32 v[92:93], v[36:37], v[82:83]
	v_pk_mul_f32 v[68:69], v[38:39], v[84:85]
	s_waitcnt vmcnt(0)
	v_pk_mul_f32 v[64:65], v[92:93], v[64:65]
	v_pk_mul_f32 v[66:67], v[68:69], v[66:67]
	v_cvt_pk_bf16_f32 v64, v64, v65
	s_and_b64 vcc, exec, s[4:5]
	v_cvt_pk_bf16_f32 v65, v66, v67
	global_store_dwordx2 v[80:81], v[64:65], off offset:512
	v_mov_b32_e32 v64, 1.0
	v_mov_b32_e32 v66, 1.0
	v_mov_b32_e32 v67, 1.0
	v_mov_b32_e32 v68, 1.0
	v_mov_b32_e32 v69, 1.0
	s_cbranch_vccnz .LBB0_192
	global_load_dwordx4 v[66:69], v[78:79], off offset:2048 nt
.LBB0_192:
	v_pk_mul_f32 v[92:93], v[40:41], v[82:83]
	v_pk_mul_f32 v[84:85], v[42:43], v[84:85]
	s_waitcnt vmcnt(0)
	v_pk_mul_f32 v[66:67], v[92:93], v[66:67]
	v_pk_mul_f32 v[68:69], v[84:85], v[68:69]
	v_cvt_pk_bf16_f32 v66, v66, v67
	s_and_b64 vcc, exec, s[4:5]
	v_cvt_pk_bf16_f32 v67, v68, v69
	global_store_dwordx2 v[80:81], v[66:67], off offset:1024
	v_mov_b32_e32 v65, 1.0
	v_mov_b32_e32 v66, 1.0
	v_mov_b32_e32 v67, 1.0
	s_cbranch_vccnz .LBB0_194
	global_load_dwordx4 v[64:67], v[78:79], off offset:3072 nt
.LBB0_194:
	v_pk_mul_f32 v[68:69], v[50:51], v[50:51]
	v_pk_mul_f32 v[84:85], v[48:49], v[48:49]
	s_and_b64 vcc, exec, s[4:5]
	v_pk_mov_b32 v[92:93], v[84:85], v[68:69] op_sel:[1,0]
	v_mov_b32_e32 v85, v69
	v_pk_add_f32 v[68:69], v[92:93], v[84:85]
	v_pk_mul_f32 v[84:85], v[54:55], v[54:55]
	v_pk_add_f32 v[68:69], v[68:69], v[68:69] op_sel_hi:[0,1]
	v_pk_mul_f32 v[92:93], v[52:53], v[52:53]
	v_mul_f32_e32 v68, v56, v56
	v_pk_mov_b32 v[94:95], v[92:93], v[84:85] op_sel:[1,0]
	v_mov_b32_e32 v93, v85
	v_pk_add_f32 v[84:85], v[94:95], v[92:93]
	v_pk_fma_f32 v[92:93], v[56:57], v[56:57], v[68:69] op_sel_hi:[1,1,0]
	v_mul_f32_e32 v68, v58, v58
	v_pk_add_f32 v[84:85], v[84:85], v[84:85] op_sel_hi:[0,1]
	v_pk_fma_f32 v[94:95], v[58:59], v[58:59], v[68:69] op_sel_hi:[1,1,0]
	v_mul_f32_e32 v92, v60, v60
	v_mul_f32_e32 v94, v61, v61
	v_mul_f32_e32 v84, v62, v62
	v_mul_f32_e32 v68, v63, v63
	v_pk_add_f32 v[92:93], v[92:93], v[94:95]
	v_pk_add_f32 v[68:69], v[84:85], v[68:69]
	s_nop 0
	v_pk_add_f32 v[68:69], v[92:93], v[68:69]
	s_nop 0
	v_add_f32_e32 v68, v68, v69
	ds_bpermute_b32 v69, v71, v68
	s_waitcnt lgkmcnt(0)
	v_add_f32_e32 v68, v68, v69
	ds_bpermute_b32 v69, v73, v68
	s_waitcnt lgkmcnt(0)
	v_add_f32_e32 v69, v68, v69
	ds_bpermute_b32 v84, v87, v69
	v_mov_b32_e32 v68, v82
	s_waitcnt lgkmcnt(0)
	v_add_f32_e32 v84, v69, v84
	ds_bpermute_b32 v85, v88, v84
	v_mov_b32_e32 v69, v82
	v_pk_mul_f32 v[68:69], v[46:47], v[68:69]
	v_pk_mul_f32 v[82:83], v[44:45], v[82:83]
	s_waitcnt vmcnt(0)
	v_pk_mul_f32 v[66:67], v[68:69], v[66:67]
	s_waitcnt lgkmcnt(0)
	v_add_f32_e32 v68, v84, v85
	ds_bpermute_b32 v69, v89, v68
	v_pk_mul_f32 v[64:65], v[82:83], v[64:65]
	s_nop 0
	v_cvt_pk_bf16_f32 v64, v64, v65
	v_cvt_pk_bf16_f32 v65, v66, v67
	global_store_dwordx2 v[80:81], v[64:65], off offset:1536
	s_waitcnt lgkmcnt(0)
	v_add_f32_e32 v65, v68, v69
	ds_bpermute_b32 v80, v90, v65
	v_mov_b32_e32 v64, 1.0
	v_mov_b32_e32 v66, 1.0
	v_mov_b32_e32 v67, 1.0
	v_mov_b32_e32 v68, 1.0
	v_mov_b32_e32 v69, 1.0
	s_cbranch_vccnz .LBB0_196
	global_load_dwordx4 v[66:69], v[78:79], off nt
.LBB0_196:
	s_waitcnt lgkmcnt(0)
	v_add_f32_e32 v65, v65, v80
	v_fmamk_f32 v65, v65, 0x3a800000, v91
	v_rsq_f32_e32 v82, v65
	s_ashr_i32 s13, s12, 31
	s_lshl_b64 s[20:21], s[12:13], 11
	v_lshl_add_u64 v[80:81], v[76:77], 0, s[20:21]
	v_pk_mul_f32 v[92:93], v[48:49], v[82:83] op_sel_hi:[1,0]
	v_pk_mul_f32 v[84:85], v[50:51], v[82:83] op_sel_hi:[1,0]
	s_waitcnt vmcnt(0)
	v_pk_mul_f32 v[66:67], v[92:93], v[66:67]
	v_pk_mul_f32 v[68:69], v[84:85], v[68:69]
	v_cvt_pk_bf16_f32 v66, v66, v67
	s_and_b64 vcc, exec, s[4:5]
	v_cvt_pk_bf16_f32 v67, v68, v69
	global_store_dwordx2 v[80:81], v[66:67], off
	v_mov_b32_e32 v65, 1.0
	v_mov_b32_e32 v66, 1.0
	v_mov_b32_e32 v67, 1.0
	s_cbranch_vccnz .LBB0_198
	global_load_dwordx4 v[64:67], v[78:79], off offset:1024 nt
.LBB0_198:
	v_mov_b32_e32 v83, v82
	v_mov_b32_e32 v84, v82
	v_mov_b32_e32 v85, v82
	v_pk_mul_f32 v[92:93], v[52:53], v[82:83]
	v_pk_mul_f32 v[68:69], v[54:55], v[84:85]
	s_waitcnt vmcnt(0)
	v_pk_mul_f32 v[64:65], v[92:93], v[64:65]
	v_pk_mul_f32 v[66:67], v[68:69], v[66:67]
	v_cvt_pk_bf16_f32 v64, v64, v65
	s_and_b64 vcc, exec, s[4:5]
	v_cvt_pk_bf16_f32 v65, v66, v67
	global_store_dwordx2 v[80:81], v[64:65], off offset:512
	v_mov_b32_e32 v64, 1.0
	v_mov_b32_e32 v66, 1.0
	v_mov_b32_e32 v67, 1.0
	v_mov_b32_e32 v68, 1.0
	v_mov_b32_e32 v69, 1.0
	s_cbranch_vccnz .LBB0_200
	global_load_dwordx4 v[66:69], v[78:79], off offset:2048 nt
.LBB0_200:
	v_pk_mul_f32 v[92:93], v[56:57], v[82:83]
	v_pk_mul_f32 v[84:85], v[58:59], v[84:85]
	s_waitcnt vmcnt(0)
	v_pk_mul_f32 v[66:67], v[92:93], v[66:67]
	v_pk_mul_f32 v[68:69], v[84:85], v[68:69]
	v_cvt_pk_bf16_f32 v66, v66, v67
	s_and_b64 vcc, exec, s[4:5]
	v_cvt_pk_bf16_f32 v67, v68, v69
	global_store_dwordx2 v[80:81], v[66:67], off offset:1024
	v_mov_b32_e32 v65, 1.0
	v_mov_b32_e32 v66, 1.0
	v_mov_b32_e32 v67, 1.0
	s_cbranch_vccnz .LBB0_163
	global_load_dwordx4 v[64:67], v[78:79], off offset:3072 nt
	s_branch .LBB0_163
.LBB0_202:
	s_waitcnt vmcnt(7)
	v_mov_b32_e32 v2, s0
	v_mov_b32_e32 v3, s1
	v_mov_b32_e32 v0, s0
	v_mov_b32_e32 v1, s1
	v_readfirstlane_b32 s8, v2
	v_readfirstlane_b32 s9, v3
	v_mov_b32_e32 v2, s0
	v_mov_b32_e32 v3, s1
	s_cmpk_gt_i32 s6, 0x7fff
	v_readfirstlane_b32 s4, v2
	v_readfirstlane_b32 s5, v3
	v_readfirstlane_b32 s10, v0
	v_readfirstlane_b32 s11, v1
	s_cbranch_scc1 .LBB0_219
	s_load_dwordx2 s[12:13], s[10:11], 0xc0
	s_load_dwordx2 s[14:15], s[8:9], 0x0
	v_mov_b32_e32 v73, 0
	v_mov_b32_e32 v71, v73
	s_mul_i32 s25, s33, 40
	s_waitcnt lgkmcnt(0)
	s_add_u32 s22, s12, 0x3720c00
	s_addc_u32 s23, s13, 0
	s_add_i32 s7, s6, s26
	s_cmp_lt_i32 s7, 0x8000
	s_cselect_b32 s8, s7, s6
	s_ashr_i32 s7, s6, 31
	v_lshl_add_u64 v[64:65], s[14:15], 0, v[72:73]
	s_lshl_b64 s[10:11], s[6:7], 12
	s_ashr_i32 s9, s8, 31
	s_waitcnt vmcnt(3)
	v_lshl_add_u64 v[16:17], v[64:65], 0, s[10:11]
	s_lshl_b64 s[10:11], s[8:9], 12
	v_lshl_add_u64 v[32:33], v[64:65], 0, s[10:11]
	global_load_dwordx4 v[0:3], v[16:17], off nt
	global_load_dwordx4 v[4:7], v[16:17], off offset:1024 nt
	global_load_dwordx4 v[8:11], v[16:17], off offset:2048 nt
	global_load_dwordx4 v[12:15], v[16:17], off offset:3072 nt
	s_nop 0
	global_load_dwordx4 v[16:19], v[32:33], off nt
	global_load_dwordx4 v[20:23], v[32:33], off offset:1024 nt
	global_load_dwordx4 v[24:27], v[32:33], off offset:2048 nt
	global_load_dwordx4 v[28:31], v[32:33], off offset:3072 nt
	s_load_dwordx2 s[4:5], s[4:5], 0xc0
	s_lshl_b32 s24, s33, 5
	s_mul_i32 s26, s33, 24
	v_mov_b32_e32 v69, 0x358637bd
	s_mov_b32 s14, s6
	s_waitcnt lgkmcnt(0)
	v_lshl_add_u64 v[32:33], s[4:5], 0, v[70:71]
	s_mov_b64 s[4:5], 0x4000000
	v_lshl_add_u64 v[66:67], v[32:33], 0, s[4:5]
	v_mbcnt_lo_u32_b32 v32, -1, 0
	v_cmp_eq_u32_e64 s[4:5], 0, v86
	v_mbcnt_hi_u32_b32 v68, -1, v32
	s_branch .LBB0_206

.LBB0_206:
	s_add_i32 s16, s6, s3
	s_cmp_lt_i32 s16, 0x8000
	s_cselect_b64 s[18:19], -1, 0
	s_cmpk_gt_i32 s16, 0x7fff
	s_cbranch_scc1 .LBB0_208
	s_add_i32 s7, s26, s6
	s_cmp_lt_i32 s7, 0x8000
	s_cselect_b32 s10, s7, s16
	s_ashr_i32 s17, s16, 31
	s_lshl_b64 s[12:13], s[16:17], 12
	s_ashr_i32 s11, s10, 31
	v_lshl_add_u64 v[48:49], v[64:65], 0, s[12:13]
	s_lshl_b64 s[12:13], s[10:11], 12
	s_waitcnt lgkmcnt(0)
	v_lshl_add_u64 v[70:71], v[64:65], 0, s[12:13]
	global_load_dwordx4 v[32:35], v[48:49], off nt
	global_load_dwordx4 v[36:39], v[48:49], off offset:1024 nt
	global_load_dwordx4 v[40:43], v[48:49], off offset:2048 nt
	global_load_dwordx4 v[44:47], v[48:49], off offset:3072 nt
	s_nop 0
	global_load_dwordx4 v[48:51], v[70:71], off nt
	global_load_dwordx4 v[52:55], v[70:71], off offset:1024 nt
	global_load_dwordx4 v[56:59], v[70:71], off offset:2048 nt
	global_load_dwordx4 v[60:63], v[70:71], off offset:3072 nt
	s_mov_b32 s12, s16

.LBB0_214:
	s_add_i32 s6, s25, s6
	s_cmp_lt_i32 s6, 0x8000
	s_cselect_b32 s8, s6, s20
	s_ashr_i32 s21, s20, 31
	s_lshl_b64 s[6:7], s[20:21], 12
	s_ashr_i32 s9, s8, 31
	v_lshl_add_u64 v[16:17], v[64:65], 0, s[6:7]
	s_lshl_b64 s[6:7], s[8:9], 12
	s_waitcnt lgkmcnt(0)
	v_lshl_add_u64 v[78:79], v[64:65], 0, s[6:7]
	global_load_dwordx4 v[0:3], v[16:17], off nt
	global_load_dwordx4 v[4:7], v[16:17], off offset:1024 nt
	global_load_dwordx4 v[8:11], v[16:17], off offset:2048 nt
	global_load_dwordx4 v[12:15], v[16:17], off offset:3072 nt
	s_nop 0
	global_load_dwordx4 v[16:19], v[78:79], off nt
	global_load_dwordx4 v[20:23], v[78:79], off offset:1024 nt
	global_load_dwordx4 v[24:27], v[78:79], off offset:2048 nt
	global_load_dwordx4 v[28:31], v[78:79], off offset:3072 nt
	s_mov_b32 s14, s20
	s_andn2_b64 vcc, exec, s[18:19]
	s_cbranch_vccnz .LBB0_205
